# out-proj epilogues (3 of 4): bf16 copy stored as 8 rows x 64B per instruction (adjacent blocks exchanged between lane halves after packing, DPP on two registers); f32 stores unchanged
# baseline (speedup 1.0000x reference)
.LBB0_522:
	s_mov_b32 s98, 0x10000
	s_mov_b32 s99, 0
	s_mov_b32 s100, 0x8000
	s_mov_b32 s101, 0
	v_bfe_u32 v255, v220, 3, 1
	v_sub_u32_e32 v255, 0, v255
	v_and_b32_e32 v254, 0xffff0040, v255
	v_lshl_add_u32 v168, s71, 8, v174
	v_lshl_or_b32 v164, s72, 8, v176
	v_readlane_b32 s72, v248, 9
	v_ashrrev_i32_e32 v165, 31, v164
	v_ashrrev_i32_e32 v169, 31, v168
	v_readlane_b32 s73, v248, 10
	v_lshlrev_b64 v[128:129], 13, v[168:169]
	v_readlane_b32 s74, v248, 11
	v_lshl_add_u64 v[166:167], v[164:165], 2, s[72:73]
	v_lshl_add_u64 v[128:129], v[166:167], 0, v[128:129]
	global_load_dwordx4 v[180:183], v[128:129], off
	global_load_dwordx4 v[184:187], v[128:129], off offset:64
	global_load_dwordx4 v[188:191], v[128:129], off offset:512
	global_load_dwordx4 v[192:195], v[128:129], off offset:576
	v_or_b32_e32 v128, 16, v168
	v_ashrrev_i32_e32 v129, 31, v128
	v_lshlrev_b64 v[130:131], 13, v[128:129]
	v_lshl_add_u64 v[130:131], v[166:167], 0, v[130:131]
	global_load_dwordx4 v[196:199], v[130:131], off
	global_load_dwordx4 v[200:203], v[130:131], off offset:64
	v_readlane_b32 s75, v248, 12
	v_readlane_b32 s76, v248, 13
	v_readlane_b32 s77, v248, 14
	v_readlane_b32 s78, v248, 15
	v_readlane_b32 s79, v248, 16
	v_or_b32_e32 v172, 32, v168
	v_readlane_b32 s72, v248, 0
	v_or_b32_e32 v170, 48, v168
	v_ashrrev_i32_e32 v173, 31, v172
	v_readlane_b32 s76, v248, 4
	v_readlane_b32 s77, v248, 5
	v_ashrrev_i32_e32 v171, 31, v170
	v_lshlrev_b64 v[132:133], 11, v[168:169]
	v_lshlrev_b64 v[134:135], 13, v[172:173]
	v_readlane_b32 s78, v248, 6
	v_readlane_b32 s79, v248, 7
	s_mov_b64 s[24:25], s[76:77]
	v_lshlrev_b64 v[136:137], 13, v[170:171]
	v_lshl_add_u64 v[132:133], v[132:133], 0, v[164:165]
	v_lshlrev_b64 v[128:129], 11, v[128:129]
	v_lshl_add_u64 v[134:135], v[166:167], 0, v[134:135]
	s_mov_b64 s[26:27], s[78:79]
	v_lshl_add_u64 v[226:227], v[166:167], 0, v[136:137]
	v_lshl_add_u64 v[228:229], v[132:133], 2, s[26:27]
	v_lshl_add_u64 v[230:231], v[132:133], 1, s[10:11]
	v_lshl_add_u64 v[232:233], v[128:129], 0, v[164:165]
	global_load_dwordx4 v[204:207], v[130:131], off offset:512
	global_load_dwordx4 v[208:211], v[130:131], off offset:576
	global_load_dwordx4 v[212:215], v[134:135], off
	global_load_dwordx4 v[216:219], v[134:135], off offset:64
	global_load_dwordx4 v[222:225], v[134:135], off offset:512
	global_load_dwordx4 v[144:147], v[134:135], off offset:576
	global_load_dwordx4 v[140:143], v[226:227], off
	global_load_dwordx4 v[136:139], v[226:227], off offset:64
	s_nop 0
	global_load_dwordx4 v[132:135], v[226:227], off offset:512
	global_load_dwordx4 v[128:131], v[226:227], off offset:576
	v_lshl_add_u64 v[226:227], v[232:233], 2, s[26:27]
	v_readlane_b32 s80, v248, 17
	v_readlane_b32 s81, v248, 18
	v_readlane_b32 s82, v248, 19
	v_readlane_b32 s83, v248, 20
	v_readlane_b32 s84, v248, 21
	v_readlane_b32 s85, v248, 22
	v_readlane_b32 s86, v248, 23
	v_readlane_b32 s87, v248, 24
	v_readlane_b32 s73, v248, 1
	v_readlane_b32 s74, v248, 2
	v_readlane_b32 s75, v248, 3
	s_waitcnt vmcnt(0)
	v_pk_add_f32 v[126:127], v[126:127], v[182:183]
	v_pk_add_f32 v[124:125], v[124:125], v[180:181]
	v_pk_add_f32 v[120:121], v[120:121], v[184:185]
	v_pk_add_f32 v[122:123], v[122:123], v[186:187]
	v_pk_add_f32 v[112:113], v[112:113], v[188:189]
	global_store_dwordx4 v[228:229], v[124:127], off
	v_mul_f32_e32 v182, v125, v125
	v_cvt_pk_bf16_f32 v180, v124, v125
	v_cvt_pk_bf16_f32 v181, v126, v127
	v_pk_add_f32 v[114:115], v[114:115], v[190:191]
	v_mul_f32_e32 v125, v121, v121
	v_pk_add_f32 v[108:109], v[108:109], v[192:193]
	v_mul_f32_e32 v183, v127, v127
	v_mul_f32_e32 v127, v123, v123
	v_mul_f32_e32 v184, v113, v113
	v_mov_b32_e32 v240, v180
	v_mov_b32_e32 v241, v181
	global_store_dwordx4 v[228:229], v[120:123], off offset:64
	v_fmac_f32_e32 v125, v120, v120
	v_pk_add_f32 v[110:111], v[110:111], v[194:195]
	v_cvt_pk_bf16_f32 v120, v120, v121
	v_cvt_pk_bf16_f32 v121, v122, v123
	v_mul_f32_e32 v185, v115, v115
	v_mul_f32_e32 v186, v109, v109
	v_fmac_f32_e32 v182, v124, v124
	v_fmac_f32_e32 v183, v126, v126
	v_fmac_f32_e32 v127, v122, v122
	v_fmac_f32_e32 v184, v112, v112
	v_mov_b32_e32 v242, v120
	v_mov_b32_e32 v243, v121
	v_mov_b32_dpp v242, v240 row_ror:8 row_mask:0xf bank_mask:0x3
	v_mov_b32_dpp v243, v241 row_ror:8 row_mask:0xf bank_mask:0x3
	v_mov_b32_dpp v240, v120 row_ror:8 row_mask:0xf bank_mask:0xc
	v_mov_b32_dpp v241, v121 row_ror:8 row_mask:0xf bank_mask:0xc
	v_ashrrev_i64 v[250:251], 1, v[254:255]
	v_lshl_add_u64 v[250:251], v[230:231], 0, v[250:251]
	v_lshl_add_u64 v[252:253], v[250:251], 0, s[100:101]
	global_store_dwordx2 v[250:251], v[240:241], off
	global_store_dwordx2 v[252:253], v[242:243], off
	global_store_dwordx4 v[228:229], v[112:115], off offset:512
	v_mul_f32_e32 v187, v111, v111
	v_pk_add_f32 v[118:119], v[118:119], v[198:199]
	v_cvt_pk_bf16_f32 v112, v112, v113
	v_cvt_pk_bf16_f32 v113, v114, v115
	v_pk_add_f32 v[116:117], v[116:117], v[196:197]
	v_fmac_f32_e32 v185, v114, v114
	v_fmac_f32_e32 v186, v108, v108
	v_add_f32_e32 v122, v182, v183
	v_add_f32_e32 v123, v125, v127
	v_mov_b32_e32 v240, v112
	v_mov_b32_e32 v241, v113
	global_store_dwordx4 v[228:229], v[108:111], off offset:576
	v_fmac_f32_e32 v187, v110, v110
	v_add_f32_e32 v120, v184, v185
	v_cvt_pk_bf16_f32 v108, v108, v109
	v_cvt_pk_bf16_f32 v109, v110, v111
	v_add_f32_e32 v115, v122, v123
	v_mov_b32_e32 v242, v108
	v_mov_b32_e32 v243, v109
	v_mov_b32_dpp v242, v240 row_ror:8 row_mask:0xf bank_mask:0x3
	v_mov_b32_dpp v243, v241 row_ror:8 row_mask:0xf bank_mask:0x3
	v_mov_b32_dpp v240, v108 row_ror:8 row_mask:0xf bank_mask:0xc
	v_mov_b32_dpp v241, v109 row_ror:8 row_mask:0xf bank_mask:0xc
	v_ashrrev_i64 v[250:251], 1, v[254:255]
	v_lshl_add_u64 v[250:251], v[230:231], 0, v[250:251]
	v_lshl_add_u64 v[252:253], v[250:251], 0, s[100:101]
	global_store_dwordx2 v[250:251], v[240:241], off offset:256
	global_store_dwordx2 v[252:253], v[242:243], off offset:256
	v_mul_f32_e32 v108, v117, v117
	v_mul_f32_e32 v109, v119, v119
	v_add_f32_e32 v114, v186, v187
	v_add_f32_e32 v110, v115, v120
	v_fmac_f32_e32 v108, v116, v116
	v_fmac_f32_e32 v109, v118, v118
	v_add_f32_e32 v112, v110, v114
	global_store_dwordx4 v[226:227], v[116:119], off
	v_add_f32_e32 v113, v108, v109
	v_cvt_pk_bf16_f32 v108, v116, v117
	v_lshl_add_u64 v[110:111], v[232:233], 1, s[10:11]
	v_pk_add_f32 v[104:105], v[104:105], v[200:201]
	v_cvt_pk_bf16_f32 v109, v118, v119
	v_mov_b32_e32 v240, v108
	v_mov_b32_e32 v241, v109
	v_pk_add_f32 v[106:107], v[106:107], v[202:203]
	v_mul_f32_e32 v108, v105, v105
	global_store_dwordx4 v[226:227], v[104:107], off offset:64
	v_fmac_f32_e32 v108, v104, v104
	v_pk_add_f32 v[100:101], v[100:101], v[204:205]
	v_cvt_pk_bf16_f32 v104, v104, v105
	v_cvt_pk_bf16_f32 v105, v106, v107
	v_mov_b32_e32 v242, v104
	v_mov_b32_e32 v243, v105
	v_mov_b32_dpp v242, v240 row_ror:8 row_mask:0xf bank_mask:0x3
	v_mov_b32_dpp v243, v241 row_ror:8 row_mask:0xf bank_mask:0x3
	v_mov_b32_dpp v240, v104 row_ror:8 row_mask:0xf bank_mask:0xc
	v_mov_b32_dpp v241, v105 row_ror:8 row_mask:0xf bank_mask:0xc
	v_ashrrev_i64 v[250:251], 1, v[254:255]
	v_lshl_add_u64 v[250:251], v[110:111], 0, v[250:251]
	v_lshl_add_u64 v[252:253], v[250:251], 0, s[100:101]
	global_store_dwordx2 v[250:251], v[240:241], off
	global_store_dwordx2 v[252:253], v[242:243], off
	v_pk_add_f32 v[102:103], v[102:103], v[206:207]
	v_mul_f32_e32 v104, v101, v101
	global_store_dwordx4 v[226:227], v[100:103], off offset:512
	v_fmac_f32_e32 v104, v100, v100
	v_pk_add_f32 v[96:97], v[96:97], v[208:209]
	v_cvt_pk_bf16_f32 v100, v100, v101
	v_cvt_pk_bf16_f32 v101, v102, v103
	v_mov_b32_e32 v240, v100
	v_mov_b32_e32 v241, v101
	v_pk_add_f32 v[98:99], v[98:99], v[210:211]
	v_mul_f32_e32 v100, v97, v97
	global_store_dwordx4 v[226:227], v[96:99], off offset:576
	v_fmac_f32_e32 v100, v96, v96
	v_mul_f32_e32 v101, v99, v99
	v_cvt_pk_bf16_f32 v96, v96, v97
	v_cvt_pk_bf16_f32 v97, v98, v99
	v_mov_b32_e32 v242, v96
	v_mov_b32_e32 v243, v97
	v_mov_b32_dpp v242, v240 row_ror:8 row_mask:0xf bank_mask:0x3
	v_mov_b32_dpp v243, v241 row_ror:8 row_mask:0xf bank_mask:0x3
	v_mov_b32_dpp v240, v96 row_ror:8 row_mask:0xf bank_mask:0xc
	v_mov_b32_dpp v241, v97 row_ror:8 row_mask:0xf bank_mask:0xc
	v_ashrrev_i64 v[250:251], 1, v[254:255]
	v_lshl_add_u64 v[250:251], v[110:111], 0, v[250:251]
	v_lshl_add_u64 v[252:253], v[250:251], 0, s[100:101]
	global_store_dwordx2 v[250:251], v[240:241], off offset:256
	global_store_dwordx2 v[252:253], v[242:243], off offset:256
	v_lshlrev_b64 v[96:97], 11, v[172:173]
	v_mul_f32_e32 v105, v103, v103
	v_fmac_f32_e32 v101, v98, v98
	v_lshl_add_u64 v[96:97], v[96:97], 0, v[164:165]
	v_pk_add_f32 v[94:95], v[94:95], v[214:215]
	v_pk_add_f32 v[92:93], v[92:93], v[212:213]
	v_fmac_f32_e32 v105, v102, v102
	v_add_f32_e32 v100, v100, v101
	v_lshl_add_u64 v[98:99], v[96:97], 2, s[26:27]
	v_mul_f32_e32 v101, v93, v93
	v_mul_f32_e32 v102, v95, v95
	global_store_dwordx4 v[98:99], v[92:95], off
	v_fmac_f32_e32 v101, v92, v92
	v_fmac_f32_e32 v102, v94, v94
	v_cvt_pk_bf16_f32 v92, v92, v93
	v_cvt_pk_bf16_f32 v93, v94, v95
	v_lshl_add_u64 v[94:95], v[96:97], 1, s[10:11]
	v_pk_add_f32 v[88:89], v[88:89], v[216:217]
	v_mov_b32_e32 v240, v92
	v_mov_b32_e32 v241, v93
	v_pk_add_f32 v[90:91], v[90:91], v[218:219]
	v_mul_f32_e32 v92, v89, v89
	global_store_dwordx4 v[98:99], v[88:91], off offset:64
	v_fmac_f32_e32 v92, v88, v88
	v_pk_add_f32 v[84:85], v[84:85], v[222:223]
	v_cvt_pk_bf16_f32 v88, v88, v89
	v_cvt_pk_bf16_f32 v89, v90, v91
	v_mov_b32_e32 v242, v88
	v_mov_b32_e32 v243, v89
	v_mov_b32_dpp v242, v240 row_ror:8 row_mask:0xf bank_mask:0x3
	v_mov_b32_dpp v243, v241 row_ror:8 row_mask:0xf bank_mask:0x3
	v_mov_b32_dpp v240, v88 row_ror:8 row_mask:0xf bank_mask:0xc
	v_mov_b32_dpp v241, v89 row_ror:8 row_mask:0xf bank_mask:0xc
	v_ashrrev_i64 v[250:251], 1, v[254:255]
	v_lshl_add_u64 v[250:251], v[94:95], 0, v[250:251]
	v_lshl_add_u64 v[252:253], v[250:251], 0, s[100:101]
	global_store_dwordx2 v[250:251], v[240:241], off
	global_store_dwordx2 v[252:253], v[242:243], off
	v_pk_add_f32 v[86:87], v[86:87], v[224:225]
	v_mul_f32_e32 v88, v85, v85
	global_store_dwordx4 v[98:99], v[84:87], off offset:512
	v_fmac_f32_e32 v88, v84, v84
	v_pk_add_f32 v[80:81], v[80:81], v[144:145]
	v_cvt_pk_bf16_f32 v84, v84, v85
	v_cvt_pk_bf16_f32 v85, v86, v87
	v_mov_b32_e32 v240, v84
	v_mov_b32_e32 v241, v85
	v_pk_add_f32 v[82:83], v[82:83], v[146:147]
	v_mul_f32_e32 v84, v81, v81
	global_store_dwordx4 v[98:99], v[80:83], off offset:576
	v_fmac_f32_e32 v84, v80, v80
	v_mul_f32_e32 v85, v83, v83
	v_cvt_pk_bf16_f32 v80, v80, v81
	v_cvt_pk_bf16_f32 v81, v82, v83
	v_mov_b32_e32 v242, v80
	v_mov_b32_e32 v243, v81
	v_mov_b32_dpp v242, v240 row_ror:8 row_mask:0xf bank_mask:0x3
	v_mov_b32_dpp v243, v241 row_ror:8 row_mask:0xf bank_mask:0x3
	v_mov_b32_dpp v240, v80 row_ror:8 row_mask:0xf bank_mask:0xc
	v_mov_b32_dpp v241, v81 row_ror:8 row_mask:0xf bank_mask:0xc
	v_ashrrev_i64 v[250:251], 1, v[254:255]
	v_lshl_add_u64 v[250:251], v[94:95], 0, v[250:251]
	v_lshl_add_u64 v[252:253], v[250:251], 0, s[100:101]
	global_store_dwordx2 v[250:251], v[240:241], off offset:256
	global_store_dwordx2 v[252:253], v[242:243], off offset:256
	v_lshlrev_b64 v[80:81], 11, v[170:171]
	v_mul_f32_e32 v89, v87, v87
	v_fmac_f32_e32 v85, v82, v82
	v_lshl_add_u64 v[80:81], v[80:81], 0, v[164:165]
	v_pk_add_f32 v[78:79], v[78:79], v[142:143]
	v_pk_add_f32 v[76:77], v[76:77], v[140:141]
	v_fmac_f32_e32 v89, v86, v86
	v_add_f32_e32 v84, v84, v85
	v_lshl_add_u64 v[82:83], v[80:81], 2, s[26:27]
	v_mul_f32_e32 v85, v77, v77
	v_mul_f32_e32 v86, v79, v79
	global_store_dwordx4 v[82:83], v[76:79], off
	v_fmac_f32_e32 v85, v76, v76
	v_fmac_f32_e32 v86, v78, v78
	v_cvt_pk_bf16_f32 v76, v76, v77
	v_cvt_pk_bf16_f32 v77, v78, v79
	v_lshl_add_u64 v[78:79], v[80:81], 1, s[10:11]
	v_pk_add_f32 v[72:73], v[72:73], v[136:137]
	v_mov_b32_e32 v240, v76
	v_mov_b32_e32 v241, v77
	v_pk_add_f32 v[74:75], v[74:75], v[138:139]
	v_mul_f32_e32 v76, v73, v73
	global_store_dwordx4 v[82:83], v[72:75], off offset:64
	v_fmac_f32_e32 v76, v72, v72
	v_mul_f32_e32 v77, v75, v75
	v_cvt_pk_bf16_f32 v72, v72, v73
	v_cvt_pk_bf16_f32 v73, v74, v75
	v_pk_add_f32 v[70:71], v[70:71], v[134:135]
	v_pk_add_f32 v[68:69], v[68:69], v[132:133]
	v_fmac_f32_e32 v77, v74, v74
	v_mov_b32_e32 v242, v72
	v_mov_b32_e32 v243, v73
	v_mov_b32_dpp v242, v240 row_ror:8 row_mask:0xf bank_mask:0x3
	v_mov_b32_dpp v243, v241 row_ror:8 row_mask:0xf bank_mask:0x3
	v_mov_b32_dpp v240, v72 row_ror:8 row_mask:0xf bank_mask:0xc
	v_mov_b32_dpp v241, v73 row_ror:8 row_mask:0xf bank_mask:0xc
	v_ashrrev_i64 v[250:251], 1, v[254:255]
	v_lshl_add_u64 v[250:251], v[78:79], 0, v[250:251]
	v_lshl_add_u64 v[252:253], v[250:251], 0, s[100:101]
	global_store_dwordx2 v[250:251], v[240:241], off
	global_store_dwordx2 v[252:253], v[242:243], off
	v_mul_f32_e32 v72, v69, v69
	v_mul_f32_e32 v73, v71, v71
	v_add_f32_e32 v85, v85, v86
	v_add_f32_e32 v76, v76, v77
	v_fmac_f32_e32 v72, v68, v68
	v_fmac_f32_e32 v73, v70, v70
	v_add_f32_e32 v76, v85, v76
	v_add_f32_e32 v72, v72, v73
	v_add_f32_e32 v76, v76, v72
	v_pk_add_f32 v[74:75], v[66:67], v[130:131]
	v_pk_add_f32 v[72:73], v[64:65], v[128:129]
	v_mul_f32_e32 v65, v75, v75
	v_mul_f32_e32 v64, v73, v73
	v_fmac_f32_e32 v64, v72, v72
	v_fmac_f32_e32 v65, v74, v74
	global_store_dwordx4 v[82:83], v[68:71], off offset:512
	v_add_f32_e32 v64, v64, v65
	v_and_b32_e32 v65, 64, v179
	v_cvt_pk_bf16_f32 v68, v68, v69
	v_cvt_pk_bf16_f32 v69, v70, v71
	v_mov_b32_e32 v240, v68
	v_mov_b32_e32 v241, v69
	v_add_f32_e32 v67, v76, v64
	v_xor_b32_e32 v64, 16, v179
	v_add_u32_e32 v68, 64, v65
	v_mul_f32_e32 v109, v107, v107
	v_mul_f32_e32 v93, v91, v91
	v_cmp_lt_i32_e32 vcc, v64, v68
	v_fmac_f32_e32 v109, v106, v106
	v_fmac_f32_e32 v93, v90, v90
	v_cndmask_b32_e32 v64, v179, v64, vcc
	v_add_f32_e32 v108, v108, v109
	v_add_f32_e32 v101, v101, v102
	v_add_f32_e32 v92, v92, v93
	v_lshlrev_b32_e32 v90, 2, v64
	v_add_f32_e32 v108, v113, v108
	v_add_f32_e32 v104, v104, v105
	v_add_f32_e32 v92, v101, v92
	v_add_f32_e32 v88, v88, v89
	ds_bpermute_b32 v69, v90, v67
	v_add_f32_e32 v104, v108, v104
	v_add_f32_e32 v88, v92, v88
	v_add_f32_e32 v100, v104, v100
	v_add_f32_e32 v84, v88, v84
	ds_bpermute_b32 v64, v90, v112
	ds_bpermute_b32 v65, v90, v100
	ds_bpermute_b32 v66, v90, v84
	s_waitcnt lgkmcnt(3)
	v_add_f32_e32 v67, v67, v69
	v_xor_b32_e32 v69, 32, v179
	v_cmp_lt_i32_e32 vcc, v69, v68
	s_waitcnt lgkmcnt(2)
	v_add_f32_e32 v64, v112, v64
	s_waitcnt lgkmcnt(1)
	v_add_f32_e32 v65, v100, v65
	v_cndmask_b32_e32 v68, v179, v69, vcc
	s_waitcnt lgkmcnt(0)
	v_add_f32_e32 v66, v84, v66
	v_lshlrev_b32_e32 v91, 2, v68
	ds_bpermute_b32 v68, v91, v64
	ds_bpermute_b32 v69, v91, v65
	ds_bpermute_b32 v70, v91, v66
	ds_bpermute_b32 v71, v91, v67
	v_lshl_add_u64 v[84:85], v[168:169], 2, s[12:13]
	global_store_dwordx4 v[82:83], v[72:75], off offset:576
	s_nop 1
	v_cvt_pk_bf16_f32 v72, v72, v73
	v_cvt_pk_bf16_f32 v73, v74, v75
	v_mov_b32_e32 v242, v72
	v_mov_b32_e32 v243, v73
	v_mov_b32_dpp v242, v240 row_ror:8 row_mask:0xf bank_mask:0x3
	v_mov_b32_dpp v243, v241 row_ror:8 row_mask:0xf bank_mask:0x3
	v_mov_b32_dpp v240, v72 row_ror:8 row_mask:0xf bank_mask:0xc
	v_mov_b32_dpp v241, v73 row_ror:8 row_mask:0xf bank_mask:0xc
	v_ashrrev_i64 v[250:251], 1, v[254:255]
	v_lshl_add_u64 v[250:251], v[78:79], 0, v[250:251]
	v_lshl_add_u64 v[252:253], v[250:251], 0, s[100:101]
	global_store_dwordx2 v[250:251], v[240:241], off offset:256
	global_store_dwordx2 v[252:253], v[242:243], off offset:256
	s_and_saveexec_b64 s[6:7], s[2:3]
	s_cbranch_execz .LBB0_524
	s_waitcnt lgkmcnt(3)
	v_add_f32_e32 v64, v64, v68
	s_waitcnt lgkmcnt(0)
	v_add_f32_e32 v67, v67, v71
	v_add_f32_e32 v66, v66, v70
	v_add_f32_e32 v65, v65, v69
	global_atomic_add_f32 v[84:85], v64, off
	global_atomic_add_f32 v[84:85], v65, off offset:64
	global_atomic_add_f32 v[84:85], v66, off offset:128
	global_atomic_add_f32 v[84:85], v67, off offset:192
.LBB0_524:
	s_or_b64 exec, exec, s[6:7]
	v_add_u32_e32 v64, 0x80, v168
	v_ashrrev_i32_e32 v65, 31, v64
	v_lshlrev_b64 v[66:67], 13, v[64:65]
	v_lshl_add_u64 v[66:67], v[166:167], 0, v[66:67]
	global_load_dwordx4 v[92:95], v[66:67], off
	global_load_dwordx4 v[96:99], v[66:67], off offset:64
	s_waitcnt lgkmcnt(3)
	v_add_u32_e32 v68, 0x90, v168
	s_waitcnt lgkmcnt(2)
	v_ashrrev_i32_e32 v69, 31, v68
	global_load_dwordx4 v[100:103], v[66:67], off offset:512
	global_load_dwordx4 v[104:107], v[66:67], off offset:576
	s_waitcnt lgkmcnt(0)
	v_lshlrev_b64 v[70:71], 13, v[68:69]
	v_lshl_add_u64 v[66:67], v[166:167], 0, v[70:71]
	global_load_dwordx4 v[108:111], v[66:67], off
	global_load_dwordx4 v[112:115], v[66:67], off offset:64
	v_add_u32_e32 v88, 0xa0, v168
	v_add_u32_e32 v86, 0xb0, v168
	v_ashrrev_i32_e32 v89, 31, v88
	v_ashrrev_i32_e32 v87, 31, v86
	v_lshlrev_b64 v[70:71], 13, v[88:89]
	v_lshlrev_b64 v[72:73], 13, v[86:87]
	v_lshlrev_b64 v[64:65], 11, v[64:65]
	v_lshlrev_b64 v[68:69], 11, v[68:69]
	v_lshl_add_u64 v[70:71], v[166:167], 0, v[70:71]
	v_lshl_add_u64 v[136:137], v[166:167], 0, v[72:73]
	v_lshl_add_u64 v[138:139], v[64:65], 0, v[164:165]
	v_lshl_add_u64 v[140:141], v[68:69], 0, v[164:165]
	global_load_dwordx4 v[116:119], v[66:67], off offset:512
	global_load_dwordx4 v[120:123], v[66:67], off offset:576
	global_load_dwordx4 v[124:127], v[70:71], off
	global_load_dwordx4 v[128:131], v[70:71], off offset:64
	global_load_dwordx4 v[132:135], v[70:71], off offset:512
	global_load_dwordx4 v[80:83], v[70:71], off offset:576
	global_load_dwordx4 v[76:79], v[136:137], off
	global_load_dwordx4 v[72:75], v[136:137], off offset:64
	s_nop 0
	global_load_dwordx4 v[68:71], v[136:137], off offset:512
	global_load_dwordx4 v[64:67], v[136:137], off offset:576
	v_readlane_b32 s72, v248, 0
	v_readlane_b32 s76, v248, 4
	v_readlane_b32 s77, v248, 5
	v_readlane_b32 s78, v248, 6
	v_readlane_b32 s79, v248, 7
	s_mov_b64 s[24:25], s[76:77]
	s_mov_b64 s[26:27], s[78:79]
	v_lshl_add_u64 v[136:137], v[138:139], 2, s[26:27]
	v_lshl_add_u64 v[138:139], v[138:139], 1, s[10:11]
	v_lshl_add_u64 v[142:143], v[140:141], 2, s[26:27]
	v_readlane_b32 s73, v248, 1
	v_readlane_b32 s74, v248, 2
	v_readlane_b32 s75, v248, 3
	s_waitcnt vmcnt(15)
	v_pk_add_f32 v[62:63], v[62:63], v[94:95]
	v_pk_add_f32 v[60:61], v[60:61], v[92:93]
	s_waitcnt vmcnt(14)
	v_pk_add_f32 v[56:57], v[56:57], v[96:97]
	v_pk_add_f32 v[58:59], v[58:59], v[98:99]
	s_waitcnt vmcnt(13)
	v_pk_add_f32 v[48:49], v[48:49], v[100:101]
	global_store_dwordx4 v[136:137], v[60:63], off
	v_mul_f32_e32 v94, v61, v61
	v_cvt_pk_bf16_f32 v92, v60, v61
	v_cvt_pk_bf16_f32 v93, v62, v63
	v_pk_add_f32 v[50:51], v[50:51], v[102:103]
	v_mul_f32_e32 v61, v57, v57
	s_waitcnt vmcnt(13)
	v_pk_add_f32 v[44:45], v[44:45], v[104:105]
	v_mul_f32_e32 v95, v63, v63
	v_mul_f32_e32 v63, v59, v59
	v_mul_f32_e32 v96, v49, v49
	v_mov_b32_e32 v240, v92
	v_mov_b32_e32 v241, v93
	global_store_dwordx4 v[136:137], v[56:59], off offset:64
	v_fmac_f32_e32 v61, v56, v56
	v_pk_add_f32 v[46:47], v[46:47], v[106:107]
	v_cvt_pk_bf16_f32 v56, v56, v57
	v_cvt_pk_bf16_f32 v57, v58, v59
	v_mul_f32_e32 v97, v51, v51
	v_mul_f32_e32 v98, v45, v45
	v_fmac_f32_e32 v94, v60, v60
	v_fmac_f32_e32 v95, v62, v62
	v_fmac_f32_e32 v63, v58, v58
	v_fmac_f32_e32 v96, v48, v48
	v_mov_b32_e32 v242, v56
	v_mov_b32_e32 v243, v57
	v_mov_b32_dpp v242, v240 row_ror:8 row_mask:0xf bank_mask:0x3
	v_mov_b32_dpp v243, v241 row_ror:8 row_mask:0xf bank_mask:0x3
	v_mov_b32_dpp v240, v56 row_ror:8 row_mask:0xf bank_mask:0xc
	v_mov_b32_dpp v241, v57 row_ror:8 row_mask:0xf bank_mask:0xc
	v_ashrrev_i64 v[250:251], 1, v[254:255]
	v_lshl_add_u64 v[250:251], v[138:139], 0, v[250:251]
	v_lshl_add_u64 v[252:253], v[250:251], 0, s[100:101]
	global_store_dwordx2 v[250:251], v[240:241], off
	global_store_dwordx2 v[252:253], v[242:243], off
	global_store_dwordx4 v[136:137], v[48:51], off offset:512
	s_waitcnt vmcnt(16)
	v_pk_add_f32 v[54:55], v[54:55], v[110:111]
	v_pk_add_f32 v[52:53], v[52:53], v[108:109]
	v_cvt_pk_bf16_f32 v48, v48, v49
	v_cvt_pk_bf16_f32 v49, v50, v51
	v_mul_f32_e32 v99, v47, v47
	v_fmac_f32_e32 v97, v50, v50
	v_fmac_f32_e32 v98, v44, v44
	v_add_f32_e32 v58, v94, v95
	v_add_f32_e32 v59, v61, v63
	v_mov_b32_e32 v240, v48
	v_mov_b32_e32 v241, v49
	global_store_dwordx4 v[136:137], v[44:47], off offset:576
	v_mul_f32_e32 v100, v53, v53
	v_fmac_f32_e32 v99, v46, v46
	v_cvt_pk_bf16_f32 v44, v44, v45
	v_cvt_pk_bf16_f32 v45, v46, v47
	v_add_f32_e32 v56, v96, v97
	v_add_f32_e32 v51, v58, v59
	v_mov_b32_e32 v242, v44
	v_mov_b32_e32 v243, v45
	v_mov_b32_dpp v242, v240 row_ror:8 row_mask:0xf bank_mask:0x3
	v_mov_b32_dpp v243, v241 row_ror:8 row_mask:0xf bank_mask:0x3
	v_mov_b32_dpp v240, v44 row_ror:8 row_mask:0xf bank_mask:0xc
	v_mov_b32_dpp v241, v45 row_ror:8 row_mask:0xf bank_mask:0xc
	v_ashrrev_i64 v[250:251], 1, v[254:255]
	v_lshl_add_u64 v[250:251], v[138:139], 0, v[250:251]
	v_lshl_add_u64 v[252:253], v[250:251], 0, s[100:101]
	global_store_dwordx2 v[250:251], v[240:241], off offset:256
	global_store_dwordx2 v[252:253], v[242:243], off offset:256
	global_store_dwordx4 v[142:143], v[52:55], off
	v_mul_f32_e32 v44, v55, v55
	v_fmac_f32_e32 v100, v52, v52
	v_add_f32_e32 v50, v98, v99
	v_add_f32_e32 v46, v51, v56
	v_fmac_f32_e32 v44, v54, v54
	v_add_f32_e32 v48, v46, v50
	v_add_f32_e32 v49, v100, v44
	v_cvt_pk_bf16_f32 v44, v52, v53
	v_lshl_add_u64 v[46:47], v[140:141], 1, s[10:11]
	s_waitcnt vmcnt(19)
	v_pk_add_f32 v[40:41], v[40:41], v[112:113]
	v_cvt_pk_bf16_f32 v45, v54, v55
	v_mov_b32_e32 v240, v44
	v_mov_b32_e32 v241, v45
	v_pk_add_f32 v[42:43], v[42:43], v[114:115]
	v_mul_f32_e32 v44, v41, v41
	global_store_dwordx4 v[142:143], v[40:43], off offset:64
	v_fmac_f32_e32 v44, v40, v40
	s_waitcnt vmcnt(19)
	v_pk_add_f32 v[36:37], v[36:37], v[116:117]
	v_cvt_pk_bf16_f32 v40, v40, v41
	v_cvt_pk_bf16_f32 v41, v42, v43
	v_mov_b32_e32 v242, v40
	v_mov_b32_e32 v243, v41
	v_mov_b32_dpp v242, v240 row_ror:8 row_mask:0xf bank_mask:0x3
	v_mov_b32_dpp v243, v241 row_ror:8 row_mask:0xf bank_mask:0x3
	v_mov_b32_dpp v240, v40 row_ror:8 row_mask:0xf bank_mask:0xc
	v_mov_b32_dpp v241, v41 row_ror:8 row_mask:0xf bank_mask:0xc
	v_ashrrev_i64 v[250:251], 1, v[254:255]
	v_lshl_add_u64 v[250:251], v[46:47], 0, v[250:251]
	v_lshl_add_u64 v[252:253], v[250:251], 0, s[100:101]
	global_store_dwordx2 v[250:251], v[240:241], off
	global_store_dwordx2 v[252:253], v[242:243], off
	v_pk_add_f32 v[38:39], v[38:39], v[118:119]
	v_mul_f32_e32 v40, v37, v37
	global_store_dwordx4 v[142:143], v[36:39], off offset:512
	v_fmac_f32_e32 v40, v36, v36
	s_waitcnt vmcnt(21)
	v_pk_add_f32 v[32:33], v[32:33], v[120:121]
	v_cvt_pk_bf16_f32 v36, v36, v37
	v_cvt_pk_bf16_f32 v37, v38, v39
	v_mov_b32_e32 v240, v36
	v_mov_b32_e32 v241, v37
	v_pk_add_f32 v[34:35], v[34:35], v[122:123]
	v_mul_f32_e32 v36, v33, v33
	global_store_dwordx4 v[142:143], v[32:35], off offset:576
	v_fmac_f32_e32 v36, v32, v32
	v_mul_f32_e32 v37, v35, v35
	v_cvt_pk_bf16_f32 v32, v32, v33
	v_cvt_pk_bf16_f32 v33, v34, v35
	v_mov_b32_e32 v242, v32
	v_mov_b32_e32 v243, v33
	v_mov_b32_dpp v242, v240 row_ror:8 row_mask:0xf bank_mask:0x3
	v_mov_b32_dpp v243, v241 row_ror:8 row_mask:0xf bank_mask:0x3
	v_mov_b32_dpp v240, v32 row_ror:8 row_mask:0xf bank_mask:0xc
	v_mov_b32_dpp v241, v33 row_ror:8 row_mask:0xf bank_mask:0xc
	v_ashrrev_i64 v[250:251], 1, v[254:255]
	v_lshl_add_u64 v[250:251], v[46:47], 0, v[250:251]
	v_lshl_add_u64 v[252:253], v[250:251], 0, s[100:101]
	global_store_dwordx2 v[250:251], v[240:241], off offset:256
	global_store_dwordx2 v[252:253], v[242:243], off offset:256
	v_lshlrev_b64 v[32:33], 11, v[88:89]
	v_mul_f32_e32 v41, v39, v39
	v_fmac_f32_e32 v37, v34, v34
	v_lshl_add_u64 v[32:33], v[32:33], 0, v[164:165]
	s_waitcnt vmcnt(23)
	v_pk_add_f32 v[30:31], v[30:31], v[126:127]
	v_pk_add_f32 v[28:29], v[28:29], v[124:125]
	v_fmac_f32_e32 v41, v38, v38
	v_add_f32_e32 v36, v36, v37
	v_lshl_add_u64 v[34:35], v[32:33], 2, s[26:27]
	v_mul_f32_e32 v37, v29, v29
	v_mul_f32_e32 v38, v31, v31
	global_store_dwordx4 v[34:35], v[28:31], off
	v_fmac_f32_e32 v37, v28, v28
	v_fmac_f32_e32 v38, v30, v30
	v_cvt_pk_bf16_f32 v28, v28, v29
	v_cvt_pk_bf16_f32 v29, v30, v31
	v_lshl_add_u64 v[30:31], v[32:33], 1, s[10:11]
	s_waitcnt vmcnt(23)
	v_pk_add_f32 v[24:25], v[24:25], v[128:129]
	v_mov_b32_e32 v240, v28
	v_mov_b32_e32 v241, v29
	v_pk_add_f32 v[26:27], v[26:27], v[130:131]
	v_mul_f32_e32 v28, v25, v25
	global_store_dwordx4 v[34:35], v[24:27], off offset:64
	v_fmac_f32_e32 v28, v24, v24
	s_waitcnt vmcnt(23)
	v_pk_add_f32 v[20:21], v[20:21], v[132:133]
	v_cvt_pk_bf16_f32 v24, v24, v25
	v_cvt_pk_bf16_f32 v25, v26, v27
	v_mov_b32_e32 v242, v24
	v_mov_b32_e32 v243, v25
	v_mov_b32_dpp v242, v240 row_ror:8 row_mask:0xf bank_mask:0x3
	v_mov_b32_dpp v243, v241 row_ror:8 row_mask:0xf bank_mask:0x3
	v_mov_b32_dpp v240, v24 row_ror:8 row_mask:0xf bank_mask:0xc
	v_mov_b32_dpp v241, v25 row_ror:8 row_mask:0xf bank_mask:0xc
	v_ashrrev_i64 v[250:251], 1, v[254:255]
	v_lshl_add_u64 v[250:251], v[30:31], 0, v[250:251]
	v_lshl_add_u64 v[252:253], v[250:251], 0, s[100:101]
	global_store_dwordx2 v[250:251], v[240:241], off
	global_store_dwordx2 v[252:253], v[242:243], off
	v_pk_add_f32 v[22:23], v[22:23], v[134:135]
	v_mul_f32_e32 v24, v21, v21
	global_store_dwordx4 v[34:35], v[20:23], off offset:512
	v_fmac_f32_e32 v24, v20, v20
	s_waitcnt vmcnt(25)
	v_pk_add_f32 v[16:17], v[16:17], v[80:81]
	v_cvt_pk_bf16_f32 v20, v20, v21
	v_cvt_pk_bf16_f32 v21, v22, v23
	v_mov_b32_e32 v240, v20
	v_mov_b32_e32 v241, v21
	v_pk_add_f32 v[18:19], v[18:19], v[82:83]
	v_mul_f32_e32 v20, v17, v17
	global_store_dwordx4 v[34:35], v[16:19], off offset:576
	v_fmac_f32_e32 v20, v16, v16
	v_mul_f32_e32 v21, v19, v19
	v_cvt_pk_bf16_f32 v16, v16, v17
	v_cvt_pk_bf16_f32 v17, v18, v19
	v_mov_b32_e32 v242, v16
	v_mov_b32_e32 v243, v17
	v_mov_b32_dpp v242, v240 row_ror:8 row_mask:0xf bank_mask:0x3
	v_mov_b32_dpp v243, v241 row_ror:8 row_mask:0xf bank_mask:0x3
	v_mov_b32_dpp v240, v16 row_ror:8 row_mask:0xf bank_mask:0xc
	v_mov_b32_dpp v241, v17 row_ror:8 row_mask:0xf bank_mask:0xc
	v_ashrrev_i64 v[250:251], 1, v[254:255]
	v_lshl_add_u64 v[250:251], v[30:31], 0, v[250:251]
	v_lshl_add_u64 v[252:253], v[250:251], 0, s[100:101]
	global_store_dwordx2 v[250:251], v[240:241], off offset:256
	global_store_dwordx2 v[252:253], v[242:243], off offset:256
	v_lshlrev_b64 v[16:17], 11, v[86:87]
	v_mul_f32_e32 v25, v23, v23
	v_fmac_f32_e32 v21, v18, v18
	v_lshl_add_u64 v[16:17], v[16:17], 0, v[164:165]
	s_waitcnt vmcnt(27)
	v_pk_add_f32 v[14:15], v[14:15], v[78:79]
	v_pk_add_f32 v[12:13], v[12:13], v[76:77]
	v_fmac_f32_e32 v25, v22, v22
	v_add_f32_e32 v20, v20, v21
	v_lshl_add_u64 v[18:19], v[16:17], 2, s[26:27]
	v_mul_f32_e32 v21, v13, v13
	v_mul_f32_e32 v22, v15, v15
	global_store_dwordx4 v[18:19], v[12:15], off
	v_fmac_f32_e32 v21, v12, v12
	v_fmac_f32_e32 v22, v14, v14
	v_cvt_pk_bf16_f32 v12, v12, v13
	v_cvt_pk_bf16_f32 v13, v14, v15
	v_lshl_add_u64 v[14:15], v[16:17], 1, s[10:11]
	s_waitcnt vmcnt(27)
	v_pk_add_f32 v[8:9], v[8:9], v[72:73]
	v_mov_b32_e32 v240, v12
	v_mov_b32_e32 v241, v13
	v_pk_add_f32 v[10:11], v[10:11], v[74:75]
	v_mul_f32_e32 v12, v9, v9
	global_store_dwordx4 v[18:19], v[8:11], off offset:64
	v_fmac_f32_e32 v12, v8, v8
	v_mul_f32_e32 v13, v11, v11
	v_cvt_pk_bf16_f32 v8, v8, v9
	v_cvt_pk_bf16_f32 v9, v10, v11
	s_waitcnt vmcnt(27)
	v_pk_add_f32 v[6:7], v[6:7], v[70:71]
	v_pk_add_f32 v[4:5], v[4:5], v[68:69]
	v_fmac_f32_e32 v13, v10, v10
	v_mov_b32_e32 v242, v8
	v_mov_b32_e32 v243, v9
	v_mov_b32_dpp v242, v240 row_ror:8 row_mask:0xf bank_mask:0x3
	v_mov_b32_dpp v243, v241 row_ror:8 row_mask:0xf bank_mask:0x3
	v_mov_b32_dpp v240, v8 row_ror:8 row_mask:0xf bank_mask:0xc
	v_mov_b32_dpp v241, v9 row_ror:8 row_mask:0xf bank_mask:0xc
	v_ashrrev_i64 v[250:251], 1, v[254:255]
	v_lshl_add_u64 v[250:251], v[14:15], 0, v[250:251]
	v_lshl_add_u64 v[252:253], v[250:251], 0, s[100:101]
	global_store_dwordx2 v[250:251], v[240:241], off
	global_store_dwordx2 v[252:253], v[242:243], off
	v_mul_f32_e32 v8, v5, v5
	v_mul_f32_e32 v9, v7, v7
	v_add_f32_e32 v21, v21, v22
	v_add_f32_e32 v12, v12, v13
	v_fmac_f32_e32 v8, v4, v4
	v_fmac_f32_e32 v9, v6, v6
	v_mul_f32_e32 v45, v43, v43
	v_mul_f32_e32 v29, v27, v27
	v_add_f32_e32 v12, v21, v12
	v_add_f32_e32 v8, v8, v9
	v_fmac_f32_e32 v45, v42, v42
	v_fmac_f32_e32 v29, v26, v26
	v_add_f32_e32 v12, v12, v8
	s_waitcnt vmcnt(28)
	v_pk_add_f32 v[10:11], v[2:3], v[66:67]
	v_pk_add_f32 v[8:9], v[0:1], v[64:65]
	v_add_f32_e32 v44, v44, v45
	v_add_f32_e32 v37, v37, v38
	v_add_f32_e32 v28, v28, v29
	v_mul_f32_e32 v0, v9, v9
	v_mul_f32_e32 v1, v11, v11
	v_add_f32_e32 v44, v49, v44
	v_add_f32_e32 v40, v40, v41
	v_add_f32_e32 v28, v37, v28
	v_add_f32_e32 v24, v24, v25
	v_fmac_f32_e32 v0, v8, v8
	v_fmac_f32_e32 v1, v10, v10
	v_add_f32_e32 v40, v44, v40
	v_add_f32_e32 v24, v28, v24
	v_add_f32_e32 v0, v0, v1
	v_add_f32_e32 v36, v40, v36
	v_add_f32_e32 v20, v24, v20
	v_add_f32_e32 v3, v12, v0
	global_store_dwordx4 v[18:19], v[4:7], off offset:512
	ds_bpermute_b32 v0, v90, v48
	ds_bpermute_b32 v1, v90, v36
	v_cvt_pk_bf16_f32 v4, v4, v5
	v_cvt_pk_bf16_f32 v5, v6, v7
	ds_bpermute_b32 v2, v90, v20
	ds_bpermute_b32 v6, v90, v3
	v_mov_b32_e32 v240, v4
	v_mov_b32_e32 v241, v5
	s_waitcnt lgkmcnt(3)
	v_add_f32_e32 v0, v48, v0
	s_waitcnt lgkmcnt(2)
	v_add_f32_e32 v1, v36, v1
	s_waitcnt lgkmcnt(1)
	v_add_f32_e32 v2, v20, v2
	s_waitcnt lgkmcnt(0)
	v_add_f32_e32 v4, v3, v6
	ds_bpermute_b32 v3, v91, v0
	ds_bpermute_b32 v5, v91, v1
	ds_bpermute_b32 v6, v91, v2
	ds_bpermute_b32 v7, v91, v4
	global_store_dwordx4 v[18:19], v[8:11], off offset:576
	s_nop 1
	v_cvt_pk_bf16_f32 v8, v8, v9
	v_cvt_pk_bf16_f32 v9, v10, v11
	v_mov_b32_e32 v242, v8
	v_mov_b32_e32 v243, v9
	v_mov_b32_dpp v242, v240 row_ror:8 row_mask:0xf bank_mask:0x3
	v_mov_b32_dpp v243, v241 row_ror:8 row_mask:0xf bank_mask:0x3
	v_mov_b32_dpp v240, v8 row_ror:8 row_mask:0xf bank_mask:0xc
	v_mov_b32_dpp v241, v9 row_ror:8 row_mask:0xf bank_mask:0xc
	v_ashrrev_i64 v[250:251], 1, v[254:255]
	v_lshl_add_u64 v[250:251], v[14:15], 0, v[250:251]
	v_lshl_add_u64 v[252:253], v[250:251], 0, s[100:101]
	global_store_dwordx2 v[250:251], v[240:241], off offset:256
	global_store_dwordx2 v[252:253], v[242:243], off offset:256
	s_and_saveexec_b64 s[6:7], s[2:3]
	s_cbranch_execz .LBB0_526
	s_waitcnt lgkmcnt(3)
	v_add_f32_e32 v0, v0, v3
	s_waitcnt lgkmcnt(0)
	v_add_f32_e32 v4, v4, v7
	v_add_f32_e32 v2, v2, v6
	v_add_f32_e32 v1, v1, v5
	global_atomic_add_f32 v[84:85], v0, off offset:512
	global_atomic_add_f32 v[84:85], v1, off offset:576
	global_atomic_add_f32 v[84:85], v2, off offset:640
	global_atomic_add_f32 v[84:85], v4, off offset:704

.LBB0_995:
	s_mov_b32 s98, 0x10000
	s_mov_b32 s99, 0
	s_mov_b32 s100, 0x8000
	s_mov_b32 s101, 0
	v_bfe_u32 v255, v220, 3, 1
	v_sub_u32_e32 v255, 0, v255
	v_and_b32_e32 v254, 0xffff0040, v255
	v_lshl_add_u32 v168, s38, 8, v180
	v_lshl_or_b32 v164, s39, 8, v182
	v_readlane_b32 s72, v248, 0
	v_ashrrev_i32_e32 v165, 31, v164
	v_ashrrev_i32_e32 v169, 31, v168
	v_readlane_b32 s78, v248, 6
	v_readlane_b32 s79, v248, 7
	v_lshlrev_b64 v[128:129], 13, v[168:169]
	v_or_b32_e32 v174, 32, v168
	v_lshl_add_u64 v[166:167], v[164:165], 2, s[78:79]
	v_lshl_add_u64 v[234:235], v[166:167], 0, v[128:129]
	v_or_b32_e32 v128, 16, v168
	v_ashrrev_i32_e32 v129, 31, v128
	global_load_dwordx4 v[188:191], v[234:235], off
	global_load_dwordx4 v[192:195], v[234:235], off offset:64
	global_load_dwordx4 v[196:199], v[234:235], off offset:512
	global_load_dwordx4 v[200:203], v[234:235], off offset:576
	v_lshlrev_b64 v[130:131], 13, v[128:129]
	v_lshl_add_u64 v[176:177], v[166:167], 0, v[130:131]
	global_load_dwordx4 v[204:207], v[176:177], off
	global_load_dwordx4 v[208:211], v[176:177], off offset:64
	v_or_b32_e32 v170, 48, v168
	v_ashrrev_i32_e32 v175, 31, v174
	v_ashrrev_i32_e32 v171, 31, v170
	v_lshlrev_b64 v[130:131], 11, v[168:169]
	v_lshlrev_b64 v[132:133], 13, v[174:175]
	v_lshlrev_b64 v[134:135], 13, v[170:171]
	v_lshl_add_u64 v[130:131], v[130:131], 0, v[164:165]
	v_lshlrev_b64 v[128:129], 11, v[128:129]
	v_lshl_add_u64 v[178:179], v[166:167], 0, v[132:133]
	v_lshl_add_u64 v[172:173], v[166:167], 0, v[134:135]
	v_lshl_add_u64 v[236:237], v[130:131], 1, s[8:9]
	v_lshl_add_u64 v[238:239], v[128:129], 0, v[164:165]
	global_load_dwordx4 v[212:215], v[176:177], off offset:512
	global_load_dwordx4 v[216:219], v[176:177], off offset:576
	global_load_dwordx4 v[222:225], v[178:179], off
	global_load_dwordx4 v[226:229], v[178:179], off offset:64
	global_load_dwordx4 v[230:233], v[178:179], off offset:512
	global_load_dwordx4 v[144:147], v[178:179], off offset:576
	global_load_dwordx4 v[140:143], v[172:173], off
	global_load_dwordx4 v[136:139], v[172:173], off offset:64
	global_load_dwordx4 v[132:135], v[172:173], off offset:512
	global_load_dwordx4 v[128:131], v[172:173], off offset:576
	v_readlane_b32 s73, v248, 1
	v_readlane_b32 s74, v248, 2
	v_readlane_b32 s75, v248, 3
	v_readlane_b32 s76, v248, 4
	v_readlane_b32 s77, v248, 5
	s_waitcnt vmcnt(0)
	v_pk_add_f32 v[126:127], v[126:127], v[190:191]
	v_pk_add_f32 v[124:125], v[124:125], v[188:189]
	v_pk_add_f32 v[120:121], v[120:121], v[192:193]
	v_pk_add_f32 v[122:123], v[122:123], v[194:195]
	v_pk_add_f32 v[112:113], v[112:113], v[196:197]
	global_store_dwordx4 v[234:235], v[124:127], off
	v_mul_f32_e32 v187, v125, v125
	v_cvt_pk_bf16_f32 v188, v124, v125
	v_cvt_pk_bf16_f32 v189, v126, v127
	v_pk_add_f32 v[114:115], v[114:115], v[198:199]
	v_mul_f32_e32 v125, v121, v121
	v_pk_add_f32 v[108:109], v[108:109], v[200:201]
	v_mul_f32_e32 v190, v127, v127
	v_mul_f32_e32 v127, v123, v123
	v_mul_f32_e32 v191, v113, v113
	v_mov_b32_e32 v240, v188
	v_mov_b32_e32 v241, v189
	global_store_dwordx4 v[234:235], v[120:123], off offset:64
	v_fmac_f32_e32 v125, v120, v120
	v_pk_add_f32 v[110:111], v[110:111], v[202:203]
	v_cvt_pk_bf16_f32 v120, v120, v121
	v_cvt_pk_bf16_f32 v121, v122, v123
	v_mul_f32_e32 v192, v115, v115
	v_mul_f32_e32 v193, v109, v109
	v_fmac_f32_e32 v187, v124, v124
	v_fmac_f32_e32 v190, v126, v126
	v_fmac_f32_e32 v127, v122, v122
	v_fmac_f32_e32 v191, v112, v112
	v_mov_b32_e32 v242, v120
	v_mov_b32_e32 v243, v121
	v_mov_b32_dpp v242, v240 row_ror:8 row_mask:0xf bank_mask:0x3
	v_mov_b32_dpp v243, v241 row_ror:8 row_mask:0xf bank_mask:0x3
	v_mov_b32_dpp v240, v120 row_ror:8 row_mask:0xf bank_mask:0xc
	v_mov_b32_dpp v241, v121 row_ror:8 row_mask:0xf bank_mask:0xc
	v_ashrrev_i64 v[250:251], 1, v[254:255]
	v_lshl_add_u64 v[250:251], v[236:237], 0, v[250:251]
	v_lshl_add_u64 v[252:253], v[250:251], 0, s[100:101]
	global_store_dwordx2 v[250:251], v[240:241], off
	global_store_dwordx2 v[252:253], v[242:243], off
	global_store_dwordx4 v[234:235], v[112:115], off offset:512
	v_mul_f32_e32 v194, v111, v111
	v_pk_add_f32 v[118:119], v[118:119], v[206:207]
	v_cvt_pk_bf16_f32 v112, v112, v113
	v_cvt_pk_bf16_f32 v113, v114, v115
	v_pk_add_f32 v[116:117], v[116:117], v[204:205]
	v_fmac_f32_e32 v192, v114, v114
	v_fmac_f32_e32 v193, v108, v108
	v_add_f32_e32 v123, v187, v190
	v_add_f32_e32 v124, v125, v127
	v_mov_b32_e32 v240, v112
	v_mov_b32_e32 v241, v113
	global_store_dwordx4 v[234:235], v[108:111], off offset:576
	v_fmac_f32_e32 v194, v110, v110
	v_mul_f32_e32 v122, v117, v117
	v_cvt_pk_bf16_f32 v108, v108, v109
	v_cvt_pk_bf16_f32 v109, v110, v111
	v_add_f32_e32 v120, v191, v192
	v_add_f32_e32 v115, v123, v124
	v_mov_b32_e32 v242, v108
	v_mov_b32_e32 v243, v109
	v_mov_b32_dpp v242, v240 row_ror:8 row_mask:0xf bank_mask:0x3
	v_mov_b32_dpp v243, v241 row_ror:8 row_mask:0xf bank_mask:0x3
	v_mov_b32_dpp v240, v108 row_ror:8 row_mask:0xf bank_mask:0xc
	v_mov_b32_dpp v241, v109 row_ror:8 row_mask:0xf bank_mask:0xc
	v_ashrrev_i64 v[250:251], 1, v[254:255]
	v_lshl_add_u64 v[250:251], v[236:237], 0, v[250:251]
	v_lshl_add_u64 v[252:253], v[250:251], 0, s[100:101]
	global_store_dwordx2 v[250:251], v[240:241], off offset:256
	global_store_dwordx2 v[252:253], v[242:243], off offset:256
	global_store_dwordx4 v[176:177], v[116:119], off
	v_mul_f32_e32 v108, v119, v119
	v_add_f32_e32 v114, v193, v194
	v_add_f32_e32 v110, v115, v120
	v_fmac_f32_e32 v122, v116, v116
	v_fmac_f32_e32 v108, v118, v118
	v_add_f32_e32 v112, v110, v114
	v_add_f32_e32 v113, v122, v108
	v_cvt_pk_bf16_f32 v108, v116, v117
	v_lshl_add_u64 v[110:111], v[238:239], 1, s[8:9]
	v_pk_add_f32 v[104:105], v[104:105], v[208:209]
	v_cvt_pk_bf16_f32 v109, v118, v119
	v_mov_b32_e32 v240, v108
	v_mov_b32_e32 v241, v109
	v_pk_add_f32 v[106:107], v[106:107], v[210:211]
	v_mul_f32_e32 v108, v105, v105
	global_store_dwordx4 v[176:177], v[104:107], off offset:64
	v_fmac_f32_e32 v108, v104, v104
	v_pk_add_f32 v[100:101], v[100:101], v[212:213]
	v_cvt_pk_bf16_f32 v104, v104, v105
	v_cvt_pk_bf16_f32 v105, v106, v107
	v_mov_b32_e32 v242, v104
	v_mov_b32_e32 v243, v105
	v_mov_b32_dpp v242, v240 row_ror:8 row_mask:0xf bank_mask:0x3
	v_mov_b32_dpp v243, v241 row_ror:8 row_mask:0xf bank_mask:0x3
	v_mov_b32_dpp v240, v104 row_ror:8 row_mask:0xf bank_mask:0xc
	v_mov_b32_dpp v241, v105 row_ror:8 row_mask:0xf bank_mask:0xc
	v_ashrrev_i64 v[250:251], 1, v[254:255]
	v_lshl_add_u64 v[250:251], v[110:111], 0, v[250:251]
	v_lshl_add_u64 v[252:253], v[250:251], 0, s[100:101]
	global_store_dwordx2 v[250:251], v[240:241], off
	global_store_dwordx2 v[252:253], v[242:243], off
	v_pk_add_f32 v[102:103], v[102:103], v[214:215]
	v_mul_f32_e32 v104, v101, v101
	global_store_dwordx4 v[176:177], v[100:103], off offset:512
	v_fmac_f32_e32 v104, v100, v100
	v_pk_add_f32 v[96:97], v[96:97], v[216:217]
	v_cvt_pk_bf16_f32 v100, v100, v101
	v_cvt_pk_bf16_f32 v101, v102, v103
	v_mov_b32_e32 v240, v100
	v_mov_b32_e32 v241, v101
	v_pk_add_f32 v[98:99], v[98:99], v[218:219]
	v_mul_f32_e32 v100, v97, v97
	global_store_dwordx4 v[176:177], v[96:99], off offset:576
	v_fmac_f32_e32 v100, v96, v96
	v_mul_f32_e32 v101, v99, v99
	v_cvt_pk_bf16_f32 v96, v96, v97
	v_cvt_pk_bf16_f32 v97, v98, v99
	v_mov_b32_e32 v242, v96
	v_mov_b32_e32 v243, v97
	v_mov_b32_dpp v242, v240 row_ror:8 row_mask:0xf bank_mask:0x3
	v_mov_b32_dpp v243, v241 row_ror:8 row_mask:0xf bank_mask:0x3
	v_mov_b32_dpp v240, v96 row_ror:8 row_mask:0xf bank_mask:0xc
	v_mov_b32_dpp v241, v97 row_ror:8 row_mask:0xf bank_mask:0xc
	v_ashrrev_i64 v[250:251], 1, v[254:255]
	v_lshl_add_u64 v[250:251], v[110:111], 0, v[250:251]
	v_lshl_add_u64 v[252:253], v[250:251], 0, s[100:101]
	global_store_dwordx2 v[250:251], v[240:241], off offset:256
	global_store_dwordx2 v[252:253], v[242:243], off offset:256
	v_lshlrev_b64 v[96:97], 11, v[174:175]
	v_pk_add_f32 v[94:95], v[94:95], v[224:225]
	v_pk_add_f32 v[92:93], v[92:93], v[222:223]
	v_fmac_f32_e32 v101, v98, v98
	v_lshl_add_u64 v[96:97], v[96:97], 0, v[164:165]
	v_mul_f32_e32 v98, v93, v93
	v_mul_f32_e32 v99, v95, v95
	global_store_dwordx4 v[178:179], v[92:95], off
	v_fmac_f32_e32 v98, v92, v92
	v_fmac_f32_e32 v99, v94, v94
	v_cvt_pk_bf16_f32 v92, v92, v93
	v_cvt_pk_bf16_f32 v93, v94, v95
	v_lshl_add_u64 v[94:95], v[96:97], 1, s[8:9]
	v_pk_add_f32 v[88:89], v[88:89], v[226:227]
	v_mov_b32_e32 v240, v92
	v_mov_b32_e32 v241, v93
	v_pk_add_f32 v[90:91], v[90:91], v[228:229]
	v_mul_f32_e32 v92, v89, v89
	global_store_dwordx4 v[178:179], v[88:91], off offset:64
	v_fmac_f32_e32 v92, v88, v88
	v_pk_add_f32 v[84:85], v[84:85], v[230:231]
	v_cvt_pk_bf16_f32 v88, v88, v89
	v_cvt_pk_bf16_f32 v89, v90, v91
	v_mov_b32_e32 v242, v88
	v_mov_b32_e32 v243, v89
	v_mov_b32_dpp v242, v240 row_ror:8 row_mask:0xf bank_mask:0x3
	v_mov_b32_dpp v243, v241 row_ror:8 row_mask:0xf bank_mask:0x3
	v_mov_b32_dpp v240, v88 row_ror:8 row_mask:0xf bank_mask:0xc
	v_mov_b32_dpp v241, v89 row_ror:8 row_mask:0xf bank_mask:0xc
	v_ashrrev_i64 v[250:251], 1, v[254:255]
	v_lshl_add_u64 v[250:251], v[94:95], 0, v[250:251]
	v_lshl_add_u64 v[252:253], v[250:251], 0, s[100:101]
	global_store_dwordx2 v[250:251], v[240:241], off
	global_store_dwordx2 v[252:253], v[242:243], off
	v_pk_add_f32 v[86:87], v[86:87], v[232:233]
	v_mul_f32_e32 v88, v85, v85
	global_store_dwordx4 v[178:179], v[84:87], off offset:512
	v_fmac_f32_e32 v88, v84, v84
	v_pk_add_f32 v[80:81], v[80:81], v[144:145]
	v_cvt_pk_bf16_f32 v84, v84, v85
	v_cvt_pk_bf16_f32 v85, v86, v87
	v_mov_b32_e32 v240, v84
	v_mov_b32_e32 v241, v85
	v_pk_add_f32 v[82:83], v[82:83], v[146:147]
	v_mul_f32_e32 v84, v81, v81
	global_store_dwordx4 v[178:179], v[80:83], off offset:576
	v_fmac_f32_e32 v84, v80, v80
	v_mul_f32_e32 v85, v83, v83
	v_cvt_pk_bf16_f32 v80, v80, v81
	v_cvt_pk_bf16_f32 v81, v82, v83
	v_mov_b32_e32 v242, v80
	v_mov_b32_e32 v243, v81
	v_mov_b32_dpp v242, v240 row_ror:8 row_mask:0xf bank_mask:0x3
	v_mov_b32_dpp v243, v241 row_ror:8 row_mask:0xf bank_mask:0x3
	v_mov_b32_dpp v240, v80 row_ror:8 row_mask:0xf bank_mask:0xc
	v_mov_b32_dpp v241, v81 row_ror:8 row_mask:0xf bank_mask:0xc
	v_ashrrev_i64 v[250:251], 1, v[254:255]
	v_lshl_add_u64 v[250:251], v[94:95], 0, v[250:251]
	v_lshl_add_u64 v[252:253], v[250:251], 0, s[100:101]
	global_store_dwordx2 v[250:251], v[240:241], off offset:256
	global_store_dwordx2 v[252:253], v[242:243], off offset:256
	v_lshlrev_b64 v[80:81], 11, v[170:171]
	v_pk_add_f32 v[78:79], v[78:79], v[142:143]
	v_pk_add_f32 v[76:77], v[76:77], v[140:141]
	v_fmac_f32_e32 v85, v82, v82
	v_lshl_add_u64 v[80:81], v[80:81], 0, v[164:165]
	v_mul_f32_e32 v82, v77, v77
	v_mul_f32_e32 v83, v79, v79
	global_store_dwordx4 v[172:173], v[76:79], off
	v_fmac_f32_e32 v82, v76, v76
	v_fmac_f32_e32 v83, v78, v78
	v_cvt_pk_bf16_f32 v76, v76, v77
	v_cvt_pk_bf16_f32 v77, v78, v79
	v_lshl_add_u64 v[78:79], v[80:81], 1, s[8:9]
	v_pk_add_f32 v[72:73], v[72:73], v[136:137]
	v_mov_b32_e32 v240, v76
	v_mov_b32_e32 v241, v77
	v_pk_add_f32 v[74:75], v[74:75], v[138:139]
	v_mul_f32_e32 v76, v73, v73
	global_store_dwordx4 v[172:173], v[72:75], off offset:64
	v_fmac_f32_e32 v76, v72, v72
	v_mul_f32_e32 v77, v75, v75
	v_cvt_pk_bf16_f32 v72, v72, v73
	v_cvt_pk_bf16_f32 v73, v74, v75
	v_pk_add_f32 v[70:71], v[70:71], v[134:135]
	v_pk_add_f32 v[68:69], v[68:69], v[132:133]
	v_fmac_f32_e32 v77, v74, v74
	v_mov_b32_e32 v242, v72
	v_mov_b32_e32 v243, v73
	v_mov_b32_dpp v242, v240 row_ror:8 row_mask:0xf bank_mask:0x3
	v_mov_b32_dpp v243, v241 row_ror:8 row_mask:0xf bank_mask:0x3
	v_mov_b32_dpp v240, v72 row_ror:8 row_mask:0xf bank_mask:0xc
	v_mov_b32_dpp v241, v73 row_ror:8 row_mask:0xf bank_mask:0xc
	v_ashrrev_i64 v[250:251], 1, v[254:255]
	v_lshl_add_u64 v[250:251], v[78:79], 0, v[250:251]
	v_lshl_add_u64 v[252:253], v[250:251], 0, s[100:101]
	global_store_dwordx2 v[250:251], v[240:241], off
	global_store_dwordx2 v[252:253], v[242:243], off
	v_mul_f32_e32 v72, v69, v69
	v_mul_f32_e32 v73, v71, v71
	v_add_f32_e32 v82, v82, v83
	v_add_f32_e32 v76, v76, v77
	v_fmac_f32_e32 v72, v68, v68
	v_fmac_f32_e32 v73, v70, v70
	v_add_f32_e32 v76, v82, v76
	v_add_f32_e32 v72, v72, v73
	v_add_f32_e32 v76, v76, v72
	v_pk_add_f32 v[74:75], v[66:67], v[130:131]
	v_pk_add_f32 v[72:73], v[64:65], v[128:129]
	v_mul_f32_e32 v65, v75, v75
	v_mul_f32_e32 v64, v73, v73
	v_fmac_f32_e32 v64, v72, v72
	v_fmac_f32_e32 v65, v74, v74
	global_store_dwordx4 v[172:173], v[68:71], off offset:512
	v_add_f32_e32 v64, v64, v65
	v_and_b32_e32 v65, 64, v186
	v_cvt_pk_bf16_f32 v68, v68, v69
	v_cvt_pk_bf16_f32 v69, v70, v71
	v_mov_b32_e32 v240, v68
	v_mov_b32_e32 v241, v69
	v_add_f32_e32 v67, v76, v64
	v_xor_b32_e32 v64, 16, v186
	v_add_u32_e32 v68, 64, v65
	v_mul_f32_e32 v109, v107, v107
	v_mul_f32_e32 v93, v91, v91
	v_cmp_lt_i32_e32 vcc, v64, v68
	v_fmac_f32_e32 v109, v106, v106
	v_mul_f32_e32 v105, v103, v103
	v_fmac_f32_e32 v93, v90, v90
	v_mul_f32_e32 v89, v87, v87
	v_cndmask_b32_e32 v64, v186, v64, vcc
	v_add_f32_e32 v108, v108, v109
	v_fmac_f32_e32 v105, v102, v102
	v_add_f32_e32 v98, v98, v99
	v_add_f32_e32 v92, v92, v93
	v_fmac_f32_e32 v89, v86, v86
	v_lshlrev_b32_e32 v96, 2, v64
	v_add_f32_e32 v108, v113, v108
	v_add_f32_e32 v104, v104, v105
	v_add_f32_e32 v92, v98, v92
	v_add_f32_e32 v88, v88, v89
	ds_bpermute_b32 v69, v96, v67
	v_add_f32_e32 v104, v108, v104
	v_add_f32_e32 v100, v100, v101
	v_add_f32_e32 v88, v92, v88
	v_add_f32_e32 v84, v84, v85
	v_add_f32_e32 v100, v104, v100
	v_add_f32_e32 v84, v88, v84
	ds_bpermute_b32 v64, v96, v112
	ds_bpermute_b32 v65, v96, v100
	ds_bpermute_b32 v66, v96, v84
	s_waitcnt lgkmcnt(3)
	v_add_f32_e32 v67, v67, v69
	v_xor_b32_e32 v69, 32, v186
	v_cmp_lt_i32_e32 vcc, v69, v68
	s_waitcnt lgkmcnt(2)
	v_add_f32_e32 v64, v112, v64
	s_waitcnt lgkmcnt(1)
	v_add_f32_e32 v65, v100, v65
	v_cndmask_b32_e32 v68, v186, v69, vcc
	s_waitcnt lgkmcnt(0)
	v_add_f32_e32 v66, v84, v66
	v_lshlrev_b32_e32 v97, 2, v68
	ds_bpermute_b32 v68, v97, v64
	ds_bpermute_b32 v69, v97, v65
	ds_bpermute_b32 v70, v97, v66
	ds_bpermute_b32 v71, v97, v67
	v_lshl_add_u64 v[84:85], v[168:169], 2, s[10:11]
	global_store_dwordx4 v[172:173], v[72:75], off offset:576
	s_nop 1
	v_cvt_pk_bf16_f32 v72, v72, v73
	v_cvt_pk_bf16_f32 v73, v74, v75
	v_mov_b32_e32 v242, v72
	v_mov_b32_e32 v243, v73
	v_mov_b32_dpp v242, v240 row_ror:8 row_mask:0xf bank_mask:0x3
	v_mov_b32_dpp v243, v241 row_ror:8 row_mask:0xf bank_mask:0x3
	v_mov_b32_dpp v240, v72 row_ror:8 row_mask:0xf bank_mask:0xc
	v_mov_b32_dpp v241, v73 row_ror:8 row_mask:0xf bank_mask:0xc
	v_ashrrev_i64 v[250:251], 1, v[254:255]
	v_lshl_add_u64 v[250:251], v[78:79], 0, v[250:251]
	v_lshl_add_u64 v[252:253], v[250:251], 0, s[100:101]
	global_store_dwordx2 v[250:251], v[240:241], off offset:256
	global_store_dwordx2 v[252:253], v[242:243], off offset:256
	s_and_saveexec_b64 s[38:39], s[2:3]
	s_cbranch_execz .LBB0_997
	s_waitcnt lgkmcnt(3)
	v_add_f32_e32 v64, v64, v68
	s_waitcnt lgkmcnt(0)
	v_add_f32_e32 v67, v67, v71
	v_add_f32_e32 v66, v66, v70
	v_add_f32_e32 v65, v65, v69
	global_atomic_add_f32 v[84:85], v64, off
	global_atomic_add_f32 v[84:85], v65, off offset:64
	global_atomic_add_f32 v[84:85], v66, off offset:128
	global_atomic_add_f32 v[84:85], v67, off offset:192
.LBB0_997:
	s_or_b64 exec, exec, s[38:39]
	v_add_u32_e32 v64, 0x80, v168
	v_ashrrev_i32_e32 v65, 31, v64
	v_lshlrev_b64 v[66:67], 13, v[64:65]
	v_lshl_add_u64 v[142:143], v[166:167], 0, v[66:67]
	global_load_dwordx4 v[98:101], v[142:143], off
	global_load_dwordx4 v[102:105], v[142:143], off offset:64
	global_load_dwordx4 v[106:109], v[142:143], off offset:512
	global_load_dwordx4 v[110:113], v[142:143], off offset:576
	v_add_u32_e32 v66, 0x90, v168
	v_ashrrev_i32_e32 v67, 31, v66
	s_waitcnt lgkmcnt(2)
	v_lshlrev_b64 v[68:69], 13, v[66:67]
	v_lshl_add_u64 v[92:93], v[166:167], 0, v[68:69]
	global_load_dwordx4 v[114:117], v[92:93], off
	global_load_dwordx4 v[118:121], v[92:93], off offset:64
	v_add_u32_e32 v90, 0xa0, v168
	v_add_u32_e32 v88, 0xb0, v168
	v_ashrrev_i32_e32 v91, 31, v90
	v_ashrrev_i32_e32 v89, 31, v88
	v_lshlrev_b64 v[68:69], 13, v[90:91]
	s_waitcnt lgkmcnt(0)
	v_lshlrev_b64 v[70:71], 13, v[88:89]
	v_lshlrev_b64 v[64:65], 11, v[64:65]
	v_lshlrev_b64 v[66:67], 11, v[66:67]
	v_lshl_add_u64 v[94:95], v[166:167], 0, v[68:69]
	v_lshl_add_u64 v[86:87], v[166:167], 0, v[70:71]
	v_lshl_add_u64 v[144:145], v[64:65], 0, v[164:165]
	v_lshl_add_u64 v[146:147], v[66:67], 0, v[164:165]
	global_load_dwordx4 v[122:125], v[92:93], off offset:512
	global_load_dwordx4 v[126:129], v[92:93], off offset:576
	global_load_dwordx4 v[130:133], v[94:95], off
	global_load_dwordx4 v[134:137], v[94:95], off offset:64
	global_load_dwordx4 v[138:141], v[94:95], off offset:512
	global_load_dwordx4 v[80:83], v[94:95], off offset:576
	global_load_dwordx4 v[76:79], v[86:87], off
	global_load_dwordx4 v[72:75], v[86:87], off offset:64
	global_load_dwordx4 v[68:71], v[86:87], off offset:512
	global_load_dwordx4 v[64:67], v[86:87], off offset:576
	v_lshl_add_u64 v[144:145], v[144:145], 1, s[8:9]
	s_waitcnt vmcnt(15)
	v_pk_add_f32 v[62:63], v[62:63], v[100:101]
	v_pk_add_f32 v[60:61], v[60:61], v[98:99]
	s_waitcnt vmcnt(14)
	v_pk_add_f32 v[58:59], v[58:59], v[104:105]
	v_pk_add_f32 v[56:57], v[56:57], v[102:103]
	s_waitcnt vmcnt(13)
	v_pk_add_f32 v[50:51], v[50:51], v[108:109]
	v_pk_add_f32 v[48:49], v[48:49], v[106:107]
	global_store_dwordx4 v[142:143], v[60:63], off
	v_mul_f32_e32 v100, v61, v61
	v_mul_f32_e32 v101, v63, v63
	v_cvt_pk_bf16_f32 v98, v60, v61
	v_cvt_pk_bf16_f32 v99, v62, v63
	v_mul_f32_e32 v61, v57, v57
	v_mul_f32_e32 v63, v59, v59
	s_waitcnt vmcnt(13)
	v_pk_add_f32 v[46:47], v[46:47], v[112:113]
	v_pk_add_f32 v[44:45], v[44:45], v[110:111]
	v_mul_f32_e32 v102, v49, v49
	v_mul_f32_e32 v103, v51, v51
	v_fmac_f32_e32 v100, v60, v60
	v_fmac_f32_e32 v101, v62, v62
	v_fmac_f32_e32 v61, v56, v56
	v_fmac_f32_e32 v63, v58, v58
	v_mul_f32_e32 v104, v45, v45
	v_mul_f32_e32 v105, v47, v47
	v_mov_b32_e32 v240, v98
	v_mov_b32_e32 v241, v99
	global_store_dwordx4 v[142:143], v[56:59], off offset:64
	v_fmac_f32_e32 v102, v48, v48
	v_fmac_f32_e32 v103, v50, v50
	v_cvt_pk_bf16_f32 v56, v56, v57
	v_cvt_pk_bf16_f32 v57, v58, v59
	v_add_f32_e32 v58, v100, v101
	v_add_f32_e32 v59, v61, v63
	v_fmac_f32_e32 v104, v44, v44
	v_fmac_f32_e32 v105, v46, v46
	v_mov_b32_e32 v242, v56
	v_mov_b32_e32 v243, v57
	v_mov_b32_dpp v242, v240 row_ror:8 row_mask:0xf bank_mask:0x3
	v_mov_b32_dpp v243, v241 row_ror:8 row_mask:0xf bank_mask:0x3
	v_mov_b32_dpp v240, v56 row_ror:8 row_mask:0xf bank_mask:0xc
	v_mov_b32_dpp v241, v57 row_ror:8 row_mask:0xf bank_mask:0xc
	v_ashrrev_i64 v[250:251], 1, v[254:255]
	v_lshl_add_u64 v[250:251], v[144:145], 0, v[250:251]
	v_lshl_add_u64 v[252:253], v[250:251], 0, s[100:101]
	global_store_dwordx2 v[250:251], v[240:241], off
	global_store_dwordx2 v[252:253], v[242:243], off
	global_store_dwordx4 v[142:143], v[48:51], off offset:512
	v_add_f32_e32 v56, v102, v103
	s_waitcnt vmcnt(16)
	v_pk_add_f32 v[54:55], v[54:55], v[116:117]
	v_cvt_pk_bf16_f32 v48, v48, v49
	v_cvt_pk_bf16_f32 v49, v50, v51
	v_add_f32_e32 v51, v58, v59
	v_add_f32_e32 v50, v104, v105
	v_mov_b32_e32 v240, v48
	v_mov_b32_e32 v241, v49
	global_store_dwordx4 v[142:143], v[44:47], off offset:576
	v_pk_add_f32 v[52:53], v[52:53], v[114:115]
	s_waitcnt vmcnt(16)
	v_pk_add_f32 v[40:41], v[40:41], v[118:119]
	v_cvt_pk_bf16_f32 v44, v44, v45
	v_cvt_pk_bf16_f32 v45, v46, v47
	v_add_f32_e32 v46, v51, v56
	v_mov_b32_e32 v242, v44
	v_mov_b32_e32 v243, v45
	v_mov_b32_dpp v242, v240 row_ror:8 row_mask:0xf bank_mask:0x3
	v_mov_b32_dpp v243, v241 row_ror:8 row_mask:0xf bank_mask:0x3
	v_mov_b32_dpp v240, v44 row_ror:8 row_mask:0xf bank_mask:0xc
	v_mov_b32_dpp v241, v45 row_ror:8 row_mask:0xf bank_mask:0xc
	v_ashrrev_i64 v[250:251], 1, v[254:255]
	v_lshl_add_u64 v[250:251], v[144:145], 0, v[250:251]
	v_lshl_add_u64 v[252:253], v[250:251], 0, s[100:101]
	global_store_dwordx2 v[250:251], v[240:241], off offset:256
	global_store_dwordx2 v[252:253], v[242:243], off offset:256
	global_store_dwordx4 v[92:93], v[52:55], off
	v_add_f32_e32 v48, v46, v50
	v_cvt_pk_bf16_f32 v44, v52, v53
	v_lshl_add_u64 v[46:47], v[146:147], 1, s[8:9]
	v_cvt_pk_bf16_f32 v45, v54, v55
	v_mov_b32_e32 v240, v44
	v_mov_b32_e32 v241, v45
	v_pk_add_f32 v[42:43], v[42:43], v[120:121]
	v_mul_f32_e32 v44, v41, v41
	global_store_dwordx4 v[92:93], v[40:43], off offset:64
	v_fmac_f32_e32 v44, v40, v40
	s_waitcnt vmcnt(19)
	v_pk_add_f32 v[36:37], v[36:37], v[122:123]
	v_cvt_pk_bf16_f32 v40, v40, v41
	v_cvt_pk_bf16_f32 v41, v42, v43
	v_mov_b32_e32 v242, v40
	v_mov_b32_e32 v243, v41
	v_mov_b32_dpp v242, v240 row_ror:8 row_mask:0xf bank_mask:0x3
	v_mov_b32_dpp v243, v241 row_ror:8 row_mask:0xf bank_mask:0x3
	v_mov_b32_dpp v240, v40 row_ror:8 row_mask:0xf bank_mask:0xc
	v_mov_b32_dpp v241, v41 row_ror:8 row_mask:0xf bank_mask:0xc
	v_ashrrev_i64 v[250:251], 1, v[254:255]
	v_lshl_add_u64 v[250:251], v[46:47], 0, v[250:251]
	v_lshl_add_u64 v[252:253], v[250:251], 0, s[100:101]
	global_store_dwordx2 v[250:251], v[240:241], off
	global_store_dwordx2 v[252:253], v[242:243], off
	v_pk_add_f32 v[38:39], v[38:39], v[124:125]
	v_mul_f32_e32 v40, v37, v37
	global_store_dwordx4 v[92:93], v[36:39], off offset:512
	v_fmac_f32_e32 v40, v36, v36
	s_waitcnt vmcnt(21)
	v_pk_add_f32 v[32:33], v[32:33], v[126:127]
	v_cvt_pk_bf16_f32 v36, v36, v37
	v_cvt_pk_bf16_f32 v37, v38, v39
	v_mov_b32_e32 v240, v36
	v_mov_b32_e32 v241, v37
	v_pk_add_f32 v[34:35], v[34:35], v[128:129]
	v_mul_f32_e32 v36, v33, v33
	global_store_dwordx4 v[92:93], v[32:35], off offset:576
	v_fmac_f32_e32 v36, v32, v32
	v_mul_f32_e32 v37, v35, v35
	v_cvt_pk_bf16_f32 v32, v32, v33
	v_cvt_pk_bf16_f32 v33, v34, v35
	v_mov_b32_e32 v242, v32
	v_mov_b32_e32 v243, v33
	v_mov_b32_dpp v242, v240 row_ror:8 row_mask:0xf bank_mask:0x3
	v_mov_b32_dpp v243, v241 row_ror:8 row_mask:0xf bank_mask:0x3
	v_mov_b32_dpp v240, v32 row_ror:8 row_mask:0xf bank_mask:0xc
	v_mov_b32_dpp v241, v33 row_ror:8 row_mask:0xf bank_mask:0xc
	v_ashrrev_i64 v[250:251], 1, v[254:255]
	v_lshl_add_u64 v[250:251], v[46:47], 0, v[250:251]
	v_lshl_add_u64 v[252:253], v[250:251], 0, s[100:101]
	global_store_dwordx2 v[250:251], v[240:241], off offset:256
	global_store_dwordx2 v[252:253], v[242:243], off offset:256
	v_lshlrev_b64 v[32:33], 11, v[90:91]
	s_waitcnt vmcnt(23)
	v_pk_add_f32 v[30:31], v[30:31], v[132:133]
	v_pk_add_f32 v[28:29], v[28:29], v[130:131]
	v_fmac_f32_e32 v37, v34, v34
	v_lshl_add_u64 v[32:33], v[32:33], 0, v[164:165]
	v_mul_f32_e32 v34, v29, v29
	v_mul_f32_e32 v35, v31, v31
	global_store_dwordx4 v[94:95], v[28:31], off
	v_fmac_f32_e32 v34, v28, v28
	v_fmac_f32_e32 v35, v30, v30
	v_cvt_pk_bf16_f32 v28, v28, v29
	v_cvt_pk_bf16_f32 v29, v30, v31
	v_lshl_add_u64 v[30:31], v[32:33], 1, s[8:9]
	s_waitcnt vmcnt(23)
	v_pk_add_f32 v[24:25], v[24:25], v[134:135]
	v_mov_b32_e32 v240, v28
	v_mov_b32_e32 v241, v29
	v_pk_add_f32 v[26:27], v[26:27], v[136:137]
	v_mul_f32_e32 v28, v25, v25
	global_store_dwordx4 v[94:95], v[24:27], off offset:64
	v_fmac_f32_e32 v28, v24, v24
	s_waitcnt vmcnt(23)
	v_pk_add_f32 v[20:21], v[20:21], v[138:139]
	v_cvt_pk_bf16_f32 v24, v24, v25
	v_cvt_pk_bf16_f32 v25, v26, v27
	v_mov_b32_e32 v242, v24
	v_mov_b32_e32 v243, v25
	v_mov_b32_dpp v242, v240 row_ror:8 row_mask:0xf bank_mask:0x3
	v_mov_b32_dpp v243, v241 row_ror:8 row_mask:0xf bank_mask:0x3
	v_mov_b32_dpp v240, v24 row_ror:8 row_mask:0xf bank_mask:0xc
	v_mov_b32_dpp v241, v25 row_ror:8 row_mask:0xf bank_mask:0xc
	v_ashrrev_i64 v[250:251], 1, v[254:255]
	v_lshl_add_u64 v[250:251], v[30:31], 0, v[250:251]
	v_lshl_add_u64 v[252:253], v[250:251], 0, s[100:101]
	global_store_dwordx2 v[250:251], v[240:241], off
	global_store_dwordx2 v[252:253], v[242:243], off
	v_pk_add_f32 v[22:23], v[22:23], v[140:141]
	v_mul_f32_e32 v24, v21, v21
	global_store_dwordx4 v[94:95], v[20:23], off offset:512
	v_fmac_f32_e32 v24, v20, v20
	s_waitcnt vmcnt(25)
	v_pk_add_f32 v[16:17], v[16:17], v[80:81]
	v_cvt_pk_bf16_f32 v20, v20, v21
	v_cvt_pk_bf16_f32 v21, v22, v23
	v_mov_b32_e32 v240, v20
	v_mov_b32_e32 v241, v21
	v_pk_add_f32 v[18:19], v[18:19], v[82:83]
	v_mul_f32_e32 v20, v17, v17
	global_store_dwordx4 v[94:95], v[16:19], off offset:576
	v_fmac_f32_e32 v20, v16, v16
	v_mul_f32_e32 v21, v19, v19
	v_cvt_pk_bf16_f32 v16, v16, v17
	v_cvt_pk_bf16_f32 v17, v18, v19
	v_mov_b32_e32 v242, v16
	v_mov_b32_e32 v243, v17
	v_mov_b32_dpp v242, v240 row_ror:8 row_mask:0xf bank_mask:0x3
	v_mov_b32_dpp v243, v241 row_ror:8 row_mask:0xf bank_mask:0x3
	v_mov_b32_dpp v240, v16 row_ror:8 row_mask:0xf bank_mask:0xc
	v_mov_b32_dpp v241, v17 row_ror:8 row_mask:0xf bank_mask:0xc
	v_ashrrev_i64 v[250:251], 1, v[254:255]
	v_lshl_add_u64 v[250:251], v[30:31], 0, v[250:251]
	v_lshl_add_u64 v[252:253], v[250:251], 0, s[100:101]
	global_store_dwordx2 v[250:251], v[240:241], off offset:256
	global_store_dwordx2 v[252:253], v[242:243], off offset:256
	v_lshlrev_b64 v[16:17], 11, v[88:89]
	s_waitcnt vmcnt(27)
	v_pk_add_f32 v[14:15], v[14:15], v[78:79]
	v_pk_add_f32 v[12:13], v[12:13], v[76:77]
	v_fmac_f32_e32 v21, v18, v18
	v_lshl_add_u64 v[16:17], v[16:17], 0, v[164:165]
	v_mul_f32_e32 v18, v13, v13
	v_mul_f32_e32 v19, v15, v15
	global_store_dwordx4 v[86:87], v[12:15], off
	v_fmac_f32_e32 v18, v12, v12
	v_fmac_f32_e32 v19, v14, v14
	v_cvt_pk_bf16_f32 v12, v12, v13
	v_cvt_pk_bf16_f32 v13, v14, v15
	v_lshl_add_u64 v[14:15], v[16:17], 1, s[8:9]
	s_waitcnt vmcnt(27)
	v_pk_add_f32 v[8:9], v[8:9], v[72:73]
	v_mov_b32_e32 v240, v12
	v_mov_b32_e32 v241, v13
	v_pk_add_f32 v[10:11], v[10:11], v[74:75]
	v_mul_f32_e32 v12, v9, v9
	global_store_dwordx4 v[86:87], v[8:11], off offset:64
	v_fmac_f32_e32 v12, v8, v8
	v_mul_f32_e32 v13, v11, v11
	v_cvt_pk_bf16_f32 v8, v8, v9
	v_cvt_pk_bf16_f32 v9, v10, v11
	s_waitcnt vmcnt(27)
	v_pk_add_f32 v[6:7], v[6:7], v[70:71]
	v_pk_add_f32 v[4:5], v[4:5], v[68:69]
	v_fmac_f32_e32 v13, v10, v10
	v_mov_b32_e32 v242, v8
	v_mov_b32_e32 v243, v9
	v_mov_b32_dpp v242, v240 row_ror:8 row_mask:0xf bank_mask:0x3
	v_mov_b32_dpp v243, v241 row_ror:8 row_mask:0xf bank_mask:0x3
	v_mov_b32_dpp v240, v8 row_ror:8 row_mask:0xf bank_mask:0xc
	v_mov_b32_dpp v241, v9 row_ror:8 row_mask:0xf bank_mask:0xc
	v_ashrrev_i64 v[250:251], 1, v[254:255]
	v_lshl_add_u64 v[250:251], v[14:15], 0, v[250:251]
	v_lshl_add_u64 v[252:253], v[250:251], 0, s[100:101]
	global_store_dwordx2 v[250:251], v[240:241], off
	global_store_dwordx2 v[252:253], v[242:243], off
	v_mul_f32_e32 v8, v5, v5
	v_mul_f32_e32 v9, v7, v7
	v_add_f32_e32 v18, v18, v19
	v_add_f32_e32 v12, v12, v13
	v_fmac_f32_e32 v8, v4, v4
	v_fmac_f32_e32 v9, v6, v6
	v_mul_f32_e32 v106, v53, v53
	v_mul_f32_e32 v107, v55, v55
	v_mul_f32_e32 v45, v43, v43
	v_mul_f32_e32 v29, v27, v27
	v_add_f32_e32 v12, v18, v12
	v_add_f32_e32 v8, v8, v9
	v_fmac_f32_e32 v106, v52, v52
	v_fmac_f32_e32 v107, v54, v54
	v_fmac_f32_e32 v45, v42, v42
	v_mul_f32_e32 v41, v39, v39
	v_fmac_f32_e32 v29, v26, v26
	v_mul_f32_e32 v25, v23, v23
	v_add_f32_e32 v12, v12, v8
	s_waitcnt vmcnt(28)
	v_pk_add_f32 v[10:11], v[2:3], v[66:67]
	v_pk_add_f32 v[8:9], v[0:1], v[64:65]
	v_add_f32_e32 v49, v106, v107
	v_add_f32_e32 v44, v44, v45
	v_fmac_f32_e32 v41, v38, v38
	v_add_f32_e32 v34, v34, v35
	v_add_f32_e32 v28, v28, v29
	v_fmac_f32_e32 v25, v22, v22
	v_mul_f32_e32 v0, v9, v9
	v_mul_f32_e32 v1, v11, v11
	v_add_f32_e32 v44, v49, v44
	v_add_f32_e32 v40, v40, v41
	v_add_f32_e32 v28, v34, v28
	v_add_f32_e32 v24, v24, v25
	v_fmac_f32_e32 v0, v8, v8
	v_fmac_f32_e32 v1, v10, v10
	v_add_f32_e32 v40, v44, v40
	v_add_f32_e32 v36, v36, v37
	v_add_f32_e32 v24, v28, v24
	v_add_f32_e32 v20, v20, v21
	v_add_f32_e32 v0, v0, v1
	v_add_f32_e32 v36, v40, v36
	v_add_f32_e32 v20, v24, v20
	v_add_f32_e32 v3, v12, v0
	global_store_dwordx4 v[86:87], v[4:7], off offset:512
	ds_bpermute_b32 v0, v96, v48
	ds_bpermute_b32 v1, v96, v36
	v_cvt_pk_bf16_f32 v4, v4, v5
	v_cvt_pk_bf16_f32 v5, v6, v7
	ds_bpermute_b32 v2, v96, v20
	ds_bpermute_b32 v6, v96, v3
	v_mov_b32_e32 v240, v4
	v_mov_b32_e32 v241, v5
	s_waitcnt lgkmcnt(3)
	v_add_f32_e32 v0, v48, v0
	s_waitcnt lgkmcnt(2)
	v_add_f32_e32 v1, v36, v1
	s_waitcnt lgkmcnt(1)
	v_add_f32_e32 v2, v20, v2
	s_waitcnt lgkmcnt(0)
	v_add_f32_e32 v4, v3, v6
	ds_bpermute_b32 v3, v97, v0
	ds_bpermute_b32 v5, v97, v1
	ds_bpermute_b32 v6, v97, v2
	ds_bpermute_b32 v7, v97, v4
	global_store_dwordx4 v[86:87], v[8:11], off offset:576
	s_nop 1
	v_cvt_pk_bf16_f32 v8, v8, v9
	v_cvt_pk_bf16_f32 v9, v10, v11
	v_mov_b32_e32 v242, v8
	v_mov_b32_e32 v243, v9
	v_mov_b32_dpp v242, v240 row_ror:8 row_mask:0xf bank_mask:0x3
	v_mov_b32_dpp v243, v241 row_ror:8 row_mask:0xf bank_mask:0x3
	v_mov_b32_dpp v240, v8 row_ror:8 row_mask:0xf bank_mask:0xc
	v_mov_b32_dpp v241, v9 row_ror:8 row_mask:0xf bank_mask:0xc
	v_ashrrev_i64 v[250:251], 1, v[254:255]
	v_lshl_add_u64 v[250:251], v[14:15], 0, v[250:251]
	v_lshl_add_u64 v[252:253], v[250:251], 0, s[100:101]
	global_store_dwordx2 v[250:251], v[240:241], off offset:256
	global_store_dwordx2 v[252:253], v[242:243], off offset:256
	s_and_saveexec_b64 s[38:39], s[2:3]
	s_cbranch_execz .LBB0_999
	s_waitcnt lgkmcnt(3)
	v_add_f32_e32 v0, v0, v3
	s_waitcnt lgkmcnt(0)
	v_add_f32_e32 v4, v4, v7
	v_add_f32_e32 v2, v2, v6
	v_add_f32_e32 v1, v1, v5
	global_atomic_add_f32 v[84:85], v0, off offset:512
	global_atomic_add_f32 v[84:85], v1, off offset:576
	global_atomic_add_f32 v[84:85], v2, off offset:640
	global_atomic_add_f32 v[84:85], v4, off offset:704

.LBB0_1476:
	s_mov_b32 s98, 0x10000
	s_mov_b32 s99, 0
	s_mov_b32 s100, 0x8000
	s_mov_b32 s101, 0
	v_bfe_u32 v255, v220, 3, 1
	v_sub_u32_e32 v255, 0, v255
	v_and_b32_e32 v254, 0xffff0040, v255
	v_lshl_add_u32 v168, s67, 8, v180
	v_lshl_or_b32 v164, s68, 8, v182
	v_readlane_b32 s68, v248, 0
	v_ashrrev_i32_e32 v165, 31, v164
	v_ashrrev_i32_e32 v169, 31, v168
	v_readlane_b32 s74, v248, 6
	v_readlane_b32 s75, v248, 7
	v_lshlrev_b64 v[128:129], 13, v[168:169]
	v_or_b32_e32 v174, 32, v168
	v_lshl_add_u64 v[166:167], v[164:165], 2, s[74:75]
	v_lshl_add_u64 v[218:219], v[166:167], 0, v[128:129]
	v_or_b32_e32 v128, 16, v168
	v_ashrrev_i32_e32 v129, 31, v128
	global_load_dwordx4 v[186:189], v[218:219], off
	global_load_dwordx4 v[190:193], v[218:219], off offset:64
	global_load_dwordx4 v[194:197], v[218:219], off offset:512
	global_load_dwordx4 v[198:201], v[218:219], off offset:576
	v_lshlrev_b64 v[130:131], 13, v[128:129]
	v_lshl_add_u64 v[176:177], v[166:167], 0, v[130:131]
	global_load_dwordx4 v[202:205], v[176:177], off
	global_load_dwordx4 v[206:209], v[176:177], off offset:64
	v_or_b32_e32 v170, 48, v168
	v_ashrrev_i32_e32 v175, 31, v174
	v_ashrrev_i32_e32 v171, 31, v170
	v_lshlrev_b64 v[130:131], 11, v[168:169]
	v_lshlrev_b64 v[132:133], 13, v[174:175]
	v_lshlrev_b64 v[134:135], 13, v[170:171]
	v_lshl_add_u64 v[130:131], v[130:131], 0, v[164:165]
	v_lshlrev_b64 v[128:129], 11, v[128:129]
	v_lshl_add_u64 v[178:179], v[166:167], 0, v[132:133]
	v_lshl_add_u64 v[172:173], v[166:167], 0, v[134:135]
	v_lshl_add_u64 v[234:235], v[130:131], 1, s[10:11]
	v_lshl_add_u64 v[236:237], v[128:129], 0, v[164:165]
	global_load_dwordx4 v[210:213], v[176:177], off offset:512
	global_load_dwordx4 v[214:217], v[176:177], off offset:576
	global_load_dwordx4 v[222:225], v[178:179], off
	global_load_dwordx4 v[226:229], v[178:179], off offset:64
	global_load_dwordx4 v[230:233], v[178:179], off offset:512
	global_load_dwordx4 v[144:147], v[178:179], off offset:576
	global_load_dwordx4 v[140:143], v[172:173], off
	global_load_dwordx4 v[136:139], v[172:173], off offset:64
	global_load_dwordx4 v[132:135], v[172:173], off offset:512
	global_load_dwordx4 v[128:131], v[172:173], off offset:576
	v_readlane_b32 s69, v248, 1
	v_readlane_b32 s70, v248, 2
	v_readlane_b32 s71, v248, 3
	v_readlane_b32 s72, v248, 4
	v_readlane_b32 s73, v248, 5
	s_waitcnt vmcnt(0)
	v_pk_add_f32 v[126:127], v[126:127], v[188:189]
	v_pk_add_f32 v[124:125], v[124:125], v[186:187]
	v_pk_add_f32 v[120:121], v[120:121], v[190:191]
	v_pk_add_f32 v[122:123], v[122:123], v[192:193]
	v_pk_add_f32 v[112:113], v[112:113], v[194:195]
	global_store_dwordx4 v[218:219], v[124:127], off
	v_mul_f32_e32 v188, v125, v125
	v_cvt_pk_bf16_f32 v186, v124, v125
	v_cvt_pk_bf16_f32 v187, v126, v127
	v_pk_add_f32 v[114:115], v[114:115], v[196:197]
	v_mul_f32_e32 v125, v121, v121
	v_pk_add_f32 v[108:109], v[108:109], v[198:199]
	v_mul_f32_e32 v189, v127, v127
	v_mul_f32_e32 v127, v123, v123
	v_mul_f32_e32 v190, v113, v113
	v_mov_b32_e32 v240, v186
	v_mov_b32_e32 v241, v187
	global_store_dwordx4 v[218:219], v[120:123], off offset:64
	v_fmac_f32_e32 v125, v120, v120
	v_pk_add_f32 v[110:111], v[110:111], v[200:201]
	v_cvt_pk_bf16_f32 v120, v120, v121
	v_cvt_pk_bf16_f32 v121, v122, v123
	v_mul_f32_e32 v191, v115, v115
	v_mul_f32_e32 v192, v109, v109
	v_fmac_f32_e32 v188, v124, v124
	v_fmac_f32_e32 v189, v126, v126
	v_fmac_f32_e32 v127, v122, v122
	v_fmac_f32_e32 v190, v112, v112
	v_mov_b32_e32 v242, v120
	v_mov_b32_e32 v243, v121
	v_mov_b32_dpp v242, v240 row_ror:8 row_mask:0xf bank_mask:0x3
	v_mov_b32_dpp v243, v241 row_ror:8 row_mask:0xf bank_mask:0x3
	v_mov_b32_dpp v240, v120 row_ror:8 row_mask:0xf bank_mask:0xc
	v_mov_b32_dpp v241, v121 row_ror:8 row_mask:0xf bank_mask:0xc
	v_ashrrev_i64 v[250:251], 1, v[254:255]
	v_lshl_add_u64 v[250:251], v[234:235], 0, v[250:251]
	v_lshl_add_u64 v[252:253], v[250:251], 0, s[100:101]
	global_store_dwordx2 v[250:251], v[240:241], off
	global_store_dwordx2 v[252:253], v[242:243], off
	global_store_dwordx4 v[218:219], v[112:115], off offset:512
	v_mul_f32_e32 v193, v111, v111
	v_pk_add_f32 v[118:119], v[118:119], v[204:205]
	v_cvt_pk_bf16_f32 v112, v112, v113
	v_cvt_pk_bf16_f32 v113, v114, v115
	v_pk_add_f32 v[116:117], v[116:117], v[202:203]
	v_fmac_f32_e32 v191, v114, v114
	v_fmac_f32_e32 v192, v108, v108
	v_add_f32_e32 v123, v188, v189
	v_add_f32_e32 v124, v125, v127
	v_mov_b32_e32 v240, v112
	v_mov_b32_e32 v241, v113
	global_store_dwordx4 v[218:219], v[108:111], off offset:576
	v_fmac_f32_e32 v193, v110, v110
	v_mul_f32_e32 v122, v117, v117
	v_cvt_pk_bf16_f32 v108, v108, v109
	v_cvt_pk_bf16_f32 v109, v110, v111
	v_add_f32_e32 v120, v190, v191
	v_add_f32_e32 v115, v123, v124
	v_mov_b32_e32 v242, v108
	v_mov_b32_e32 v243, v109
	v_mov_b32_dpp v242, v240 row_ror:8 row_mask:0xf bank_mask:0x3
	v_mov_b32_dpp v243, v241 row_ror:8 row_mask:0xf bank_mask:0x3
	v_mov_b32_dpp v240, v108 row_ror:8 row_mask:0xf bank_mask:0xc
	v_mov_b32_dpp v241, v109 row_ror:8 row_mask:0xf bank_mask:0xc
	v_ashrrev_i64 v[250:251], 1, v[254:255]
	v_lshl_add_u64 v[250:251], v[234:235], 0, v[250:251]
	v_lshl_add_u64 v[252:253], v[250:251], 0, s[100:101]
	global_store_dwordx2 v[250:251], v[240:241], off offset:256
	global_store_dwordx2 v[252:253], v[242:243], off offset:256
	global_store_dwordx4 v[176:177], v[116:119], off
	v_mul_f32_e32 v108, v119, v119
	v_add_f32_e32 v114, v192, v193
	v_add_f32_e32 v110, v115, v120
	v_fmac_f32_e32 v122, v116, v116
	v_fmac_f32_e32 v108, v118, v118
	v_add_f32_e32 v112, v110, v114
	v_add_f32_e32 v113, v122, v108
	v_cvt_pk_bf16_f32 v108, v116, v117
	v_lshl_add_u64 v[110:111], v[236:237], 1, s[10:11]
	v_pk_add_f32 v[104:105], v[104:105], v[206:207]
	v_cvt_pk_bf16_f32 v109, v118, v119
	v_mov_b32_e32 v240, v108
	v_mov_b32_e32 v241, v109
	v_pk_add_f32 v[106:107], v[106:107], v[208:209]
	v_mul_f32_e32 v108, v105, v105
	global_store_dwordx4 v[176:177], v[104:107], off offset:64
	v_fmac_f32_e32 v108, v104, v104
	v_pk_add_f32 v[100:101], v[100:101], v[210:211]
	v_cvt_pk_bf16_f32 v104, v104, v105
	v_cvt_pk_bf16_f32 v105, v106, v107
	v_mov_b32_e32 v242, v104
	v_mov_b32_e32 v243, v105
	v_mov_b32_dpp v242, v240 row_ror:8 row_mask:0xf bank_mask:0x3
	v_mov_b32_dpp v243, v241 row_ror:8 row_mask:0xf bank_mask:0x3
	v_mov_b32_dpp v240, v104 row_ror:8 row_mask:0xf bank_mask:0xc
	v_mov_b32_dpp v241, v105 row_ror:8 row_mask:0xf bank_mask:0xc
	v_ashrrev_i64 v[250:251], 1, v[254:255]
	v_lshl_add_u64 v[250:251], v[110:111], 0, v[250:251]
	v_lshl_add_u64 v[252:253], v[250:251], 0, s[100:101]
	global_store_dwordx2 v[250:251], v[240:241], off
	global_store_dwordx2 v[252:253], v[242:243], off
	v_pk_add_f32 v[102:103], v[102:103], v[212:213]
	v_mul_f32_e32 v104, v101, v101
	global_store_dwordx4 v[176:177], v[100:103], off offset:512
	v_fmac_f32_e32 v104, v100, v100
	v_pk_add_f32 v[96:97], v[96:97], v[214:215]
	v_cvt_pk_bf16_f32 v100, v100, v101
	v_cvt_pk_bf16_f32 v101, v102, v103
	v_mov_b32_e32 v240, v100
	v_mov_b32_e32 v241, v101
	v_pk_add_f32 v[98:99], v[98:99], v[216:217]
	v_mul_f32_e32 v100, v97, v97
	global_store_dwordx4 v[176:177], v[96:99], off offset:576
	v_fmac_f32_e32 v100, v96, v96
	v_mul_f32_e32 v101, v99, v99
	v_cvt_pk_bf16_f32 v96, v96, v97
	v_cvt_pk_bf16_f32 v97, v98, v99
	v_mov_b32_e32 v242, v96
	v_mov_b32_e32 v243, v97
	v_mov_b32_dpp v242, v240 row_ror:8 row_mask:0xf bank_mask:0x3
	v_mov_b32_dpp v243, v241 row_ror:8 row_mask:0xf bank_mask:0x3
	v_mov_b32_dpp v240, v96 row_ror:8 row_mask:0xf bank_mask:0xc
	v_mov_b32_dpp v241, v97 row_ror:8 row_mask:0xf bank_mask:0xc
	v_ashrrev_i64 v[250:251], 1, v[254:255]
	v_lshl_add_u64 v[250:251], v[110:111], 0, v[250:251]
	v_lshl_add_u64 v[252:253], v[250:251], 0, s[100:101]
	global_store_dwordx2 v[250:251], v[240:241], off offset:256
	global_store_dwordx2 v[252:253], v[242:243], off offset:256
	v_lshlrev_b64 v[96:97], 11, v[174:175]
	v_pk_add_f32 v[94:95], v[94:95], v[224:225]
	v_pk_add_f32 v[92:93], v[92:93], v[222:223]
	v_fmac_f32_e32 v101, v98, v98
	v_lshl_add_u64 v[96:97], v[96:97], 0, v[164:165]
	v_mul_f32_e32 v98, v93, v93
	v_mul_f32_e32 v99, v95, v95
	global_store_dwordx4 v[178:179], v[92:95], off
	v_fmac_f32_e32 v98, v92, v92
	v_fmac_f32_e32 v99, v94, v94
	v_cvt_pk_bf16_f32 v92, v92, v93
	v_cvt_pk_bf16_f32 v93, v94, v95
	v_lshl_add_u64 v[94:95], v[96:97], 1, s[10:11]
	v_pk_add_f32 v[88:89], v[88:89], v[226:227]
	v_mov_b32_e32 v240, v92
	v_mov_b32_e32 v241, v93
	v_pk_add_f32 v[90:91], v[90:91], v[228:229]
	v_mul_f32_e32 v92, v89, v89
	global_store_dwordx4 v[178:179], v[88:91], off offset:64
	v_fmac_f32_e32 v92, v88, v88
	v_pk_add_f32 v[84:85], v[84:85], v[230:231]
	v_cvt_pk_bf16_f32 v88, v88, v89
	v_cvt_pk_bf16_f32 v89, v90, v91
	v_mov_b32_e32 v242, v88
	v_mov_b32_e32 v243, v89
	v_mov_b32_dpp v242, v240 row_ror:8 row_mask:0xf bank_mask:0x3
	v_mov_b32_dpp v243, v241 row_ror:8 row_mask:0xf bank_mask:0x3
	v_mov_b32_dpp v240, v88 row_ror:8 row_mask:0xf bank_mask:0xc
	v_mov_b32_dpp v241, v89 row_ror:8 row_mask:0xf bank_mask:0xc
	v_ashrrev_i64 v[250:251], 1, v[254:255]
	v_lshl_add_u64 v[250:251], v[94:95], 0, v[250:251]
	v_lshl_add_u64 v[252:253], v[250:251], 0, s[100:101]
	global_store_dwordx2 v[250:251], v[240:241], off
	global_store_dwordx2 v[252:253], v[242:243], off
	v_pk_add_f32 v[86:87], v[86:87], v[232:233]
	v_mul_f32_e32 v88, v85, v85
	global_store_dwordx4 v[178:179], v[84:87], off offset:512
	v_fmac_f32_e32 v88, v84, v84
	v_pk_add_f32 v[80:81], v[80:81], v[144:145]
	v_cvt_pk_bf16_f32 v84, v84, v85
	v_cvt_pk_bf16_f32 v85, v86, v87
	v_mov_b32_e32 v240, v84
	v_mov_b32_e32 v241, v85
	v_pk_add_f32 v[82:83], v[82:83], v[146:147]
	v_mul_f32_e32 v84, v81, v81
	global_store_dwordx4 v[178:179], v[80:83], off offset:576
	v_fmac_f32_e32 v84, v80, v80
	v_mul_f32_e32 v85, v83, v83
	v_cvt_pk_bf16_f32 v80, v80, v81
	v_cvt_pk_bf16_f32 v81, v82, v83
	v_mov_b32_e32 v242, v80
	v_mov_b32_e32 v243, v81
	v_mov_b32_dpp v242, v240 row_ror:8 row_mask:0xf bank_mask:0x3
	v_mov_b32_dpp v243, v241 row_ror:8 row_mask:0xf bank_mask:0x3
	v_mov_b32_dpp v240, v80 row_ror:8 row_mask:0xf bank_mask:0xc
	v_mov_b32_dpp v241, v81 row_ror:8 row_mask:0xf bank_mask:0xc
	v_ashrrev_i64 v[250:251], 1, v[254:255]
	v_lshl_add_u64 v[250:251], v[94:95], 0, v[250:251]
	v_lshl_add_u64 v[252:253], v[250:251], 0, s[100:101]
	global_store_dwordx2 v[250:251], v[240:241], off offset:256
	global_store_dwordx2 v[252:253], v[242:243], off offset:256
	v_lshlrev_b64 v[80:81], 11, v[170:171]
	v_pk_add_f32 v[78:79], v[78:79], v[142:143]
	v_pk_add_f32 v[76:77], v[76:77], v[140:141]
	v_fmac_f32_e32 v85, v82, v82
	v_lshl_add_u64 v[80:81], v[80:81], 0, v[164:165]
	v_mul_f32_e32 v82, v77, v77
	v_mul_f32_e32 v83, v79, v79
	global_store_dwordx4 v[172:173], v[76:79], off
	v_fmac_f32_e32 v82, v76, v76
	v_fmac_f32_e32 v83, v78, v78
	v_cvt_pk_bf16_f32 v76, v76, v77
	v_cvt_pk_bf16_f32 v77, v78, v79
	v_lshl_add_u64 v[78:79], v[80:81], 1, s[10:11]
	v_pk_add_f32 v[72:73], v[72:73], v[136:137]
	v_mov_b32_e32 v240, v76
	v_mov_b32_e32 v241, v77
	v_pk_add_f32 v[74:75], v[74:75], v[138:139]
	v_mul_f32_e32 v76, v73, v73
	global_store_dwordx4 v[172:173], v[72:75], off offset:64
	v_fmac_f32_e32 v76, v72, v72
	v_mul_f32_e32 v77, v75, v75
	v_cvt_pk_bf16_f32 v72, v72, v73
	v_cvt_pk_bf16_f32 v73, v74, v75
	v_pk_add_f32 v[70:71], v[70:71], v[134:135]
	v_pk_add_f32 v[68:69], v[68:69], v[132:133]
	v_fmac_f32_e32 v77, v74, v74
	v_mov_b32_e32 v242, v72
	v_mov_b32_e32 v243, v73
	v_mov_b32_dpp v242, v240 row_ror:8 row_mask:0xf bank_mask:0x3
	v_mov_b32_dpp v243, v241 row_ror:8 row_mask:0xf bank_mask:0x3
	v_mov_b32_dpp v240, v72 row_ror:8 row_mask:0xf bank_mask:0xc
	v_mov_b32_dpp v241, v73 row_ror:8 row_mask:0xf bank_mask:0xc
	v_ashrrev_i64 v[250:251], 1, v[254:255]
	v_lshl_add_u64 v[250:251], v[78:79], 0, v[250:251]
	v_lshl_add_u64 v[252:253], v[250:251], 0, s[100:101]
	global_store_dwordx2 v[250:251], v[240:241], off
	global_store_dwordx2 v[252:253], v[242:243], off
	v_mul_f32_e32 v72, v69, v69
	v_mul_f32_e32 v73, v71, v71
	v_add_f32_e32 v82, v82, v83
	v_add_f32_e32 v76, v76, v77
	v_fmac_f32_e32 v72, v68, v68
	v_fmac_f32_e32 v73, v70, v70
	v_add_f32_e32 v76, v82, v76
	v_add_f32_e32 v72, v72, v73
	v_add_f32_e32 v76, v76, v72
	v_pk_add_f32 v[74:75], v[66:67], v[130:131]
	v_pk_add_f32 v[72:73], v[64:65], v[128:129]
	v_mul_f32_e32 v65, v75, v75
	v_mul_f32_e32 v64, v73, v73
	v_fmac_f32_e32 v64, v72, v72
	v_fmac_f32_e32 v65, v74, v74
	global_store_dwordx4 v[172:173], v[68:71], off offset:512
	v_add_f32_e32 v64, v64, v65
	v_and_b32_e32 v65, 64, v185
	v_cvt_pk_bf16_f32 v68, v68, v69
	v_cvt_pk_bf16_f32 v69, v70, v71
	v_mov_b32_e32 v240, v68
	v_mov_b32_e32 v241, v69
	v_add_f32_e32 v67, v76, v64
	v_xor_b32_e32 v64, 16, v185
	v_add_u32_e32 v68, 64, v65
	v_mul_f32_e32 v109, v107, v107
	v_mul_f32_e32 v93, v91, v91
	v_cmp_lt_i32_e32 vcc, v64, v68
	v_fmac_f32_e32 v109, v106, v106
	v_mul_f32_e32 v105, v103, v103
	v_fmac_f32_e32 v93, v90, v90
	v_mul_f32_e32 v89, v87, v87
	v_cndmask_b32_e32 v64, v185, v64, vcc
	v_add_f32_e32 v108, v108, v109
	v_fmac_f32_e32 v105, v102, v102
	v_add_f32_e32 v98, v98, v99
	v_add_f32_e32 v92, v92, v93
	v_fmac_f32_e32 v89, v86, v86
	v_lshlrev_b32_e32 v96, 2, v64
	v_add_f32_e32 v108, v113, v108
	v_add_f32_e32 v104, v104, v105
	v_add_f32_e32 v92, v98, v92
	v_add_f32_e32 v88, v88, v89
	ds_bpermute_b32 v69, v96, v67
	v_add_f32_e32 v104, v108, v104
	v_add_f32_e32 v100, v100, v101
	v_add_f32_e32 v88, v92, v88
	v_add_f32_e32 v84, v84, v85
	v_add_f32_e32 v100, v104, v100
	v_add_f32_e32 v84, v88, v84
	ds_bpermute_b32 v64, v96, v112
	ds_bpermute_b32 v65, v96, v100
	ds_bpermute_b32 v66, v96, v84
	s_waitcnt lgkmcnt(3)
	v_add_f32_e32 v67, v67, v69
	v_xor_b32_e32 v69, 32, v185
	v_cmp_lt_i32_e32 vcc, v69, v68
	s_waitcnt lgkmcnt(2)
	v_add_f32_e32 v64, v112, v64
	s_waitcnt lgkmcnt(1)
	v_add_f32_e32 v65, v100, v65
	v_cndmask_b32_e32 v68, v185, v69, vcc
	s_waitcnt lgkmcnt(0)
	v_add_f32_e32 v66, v84, v66
	v_lshlrev_b32_e32 v97, 2, v68
	ds_bpermute_b32 v68, v97, v64
	ds_bpermute_b32 v69, v97, v65
	ds_bpermute_b32 v70, v97, v66
	ds_bpermute_b32 v71, v97, v67
	v_lshl_add_u64 v[84:85], v[168:169], 2, s[12:13]
	global_store_dwordx4 v[172:173], v[72:75], off offset:576
	s_nop 1
	v_cvt_pk_bf16_f32 v72, v72, v73
	v_cvt_pk_bf16_f32 v73, v74, v75
	v_mov_b32_e32 v242, v72
	v_mov_b32_e32 v243, v73
	v_mov_b32_dpp v242, v240 row_ror:8 row_mask:0xf bank_mask:0x3
	v_mov_b32_dpp v243, v241 row_ror:8 row_mask:0xf bank_mask:0x3
	v_mov_b32_dpp v240, v72 row_ror:8 row_mask:0xf bank_mask:0xc
	v_mov_b32_dpp v241, v73 row_ror:8 row_mask:0xf bank_mask:0xc
	v_ashrrev_i64 v[250:251], 1, v[254:255]
	v_lshl_add_u64 v[250:251], v[78:79], 0, v[250:251]
	v_lshl_add_u64 v[252:253], v[250:251], 0, s[100:101]
	global_store_dwordx2 v[250:251], v[240:241], off offset:256
	global_store_dwordx2 v[252:253], v[242:243], off offset:256
	s_and_saveexec_b64 s[6:7], s[2:3]
	s_cbranch_execz .LBB0_1478
	s_waitcnt lgkmcnt(3)
	v_add_f32_e32 v64, v64, v68
	s_waitcnt lgkmcnt(0)
	v_add_f32_e32 v67, v67, v71
	v_add_f32_e32 v66, v66, v70
	v_add_f32_e32 v65, v65, v69
	global_atomic_add_f32 v[84:85], v64, off
	global_atomic_add_f32 v[84:85], v65, off offset:64
	global_atomic_add_f32 v[84:85], v66, off offset:128
	global_atomic_add_f32 v[84:85], v67, off offset:192
.LBB0_1478:
	s_or_b64 exec, exec, s[6:7]
	v_add_u32_e32 v64, 0x80, v168
	v_ashrrev_i32_e32 v65, 31, v64
	v_lshlrev_b64 v[66:67], 13, v[64:65]
	v_lshl_add_u64 v[142:143], v[166:167], 0, v[66:67]
	global_load_dwordx4 v[98:101], v[142:143], off
	global_load_dwordx4 v[102:105], v[142:143], off offset:64
	global_load_dwordx4 v[106:109], v[142:143], off offset:512
	global_load_dwordx4 v[110:113], v[142:143], off offset:576
	v_add_u32_e32 v66, 0x90, v168
	v_ashrrev_i32_e32 v67, 31, v66
	s_waitcnt lgkmcnt(2)
	v_lshlrev_b64 v[68:69], 13, v[66:67]
	v_lshl_add_u64 v[92:93], v[166:167], 0, v[68:69]
	global_load_dwordx4 v[114:117], v[92:93], off
	global_load_dwordx4 v[118:121], v[92:93], off offset:64
	v_add_u32_e32 v90, 0xa0, v168
	v_add_u32_e32 v88, 0xb0, v168
	v_ashrrev_i32_e32 v91, 31, v90
	v_ashrrev_i32_e32 v89, 31, v88
	v_lshlrev_b64 v[68:69], 13, v[90:91]
	s_waitcnt lgkmcnt(0)
	v_lshlrev_b64 v[70:71], 13, v[88:89]
	v_lshlrev_b64 v[64:65], 11, v[64:65]
	v_lshlrev_b64 v[66:67], 11, v[66:67]
	v_lshl_add_u64 v[94:95], v[166:167], 0, v[68:69]
	v_lshl_add_u64 v[86:87], v[166:167], 0, v[70:71]
	v_lshl_add_u64 v[144:145], v[64:65], 0, v[164:165]
	v_lshl_add_u64 v[146:147], v[66:67], 0, v[164:165]
	global_load_dwordx4 v[122:125], v[92:93], off offset:512
	global_load_dwordx4 v[126:129], v[92:93], off offset:576
	global_load_dwordx4 v[130:133], v[94:95], off
	global_load_dwordx4 v[134:137], v[94:95], off offset:64
	global_load_dwordx4 v[138:141], v[94:95], off offset:512
	global_load_dwordx4 v[80:83], v[94:95], off offset:576
	global_load_dwordx4 v[76:79], v[86:87], off
	global_load_dwordx4 v[72:75], v[86:87], off offset:64
	global_load_dwordx4 v[68:71], v[86:87], off offset:512
	global_load_dwordx4 v[64:67], v[86:87], off offset:576
	v_lshl_add_u64 v[144:145], v[144:145], 1, s[10:11]
	s_waitcnt vmcnt(15)
	v_pk_add_f32 v[62:63], v[62:63], v[100:101]
	v_pk_add_f32 v[60:61], v[60:61], v[98:99]
	s_waitcnt vmcnt(14)
	v_pk_add_f32 v[58:59], v[58:59], v[104:105]
	v_pk_add_f32 v[56:57], v[56:57], v[102:103]
	s_waitcnt vmcnt(13)
	v_pk_add_f32 v[50:51], v[50:51], v[108:109]
	v_pk_add_f32 v[48:49], v[48:49], v[106:107]
	global_store_dwordx4 v[142:143], v[60:63], off
	v_mul_f32_e32 v100, v61, v61
	v_mul_f32_e32 v101, v63, v63
	v_cvt_pk_bf16_f32 v98, v60, v61
	v_cvt_pk_bf16_f32 v99, v62, v63
	v_mul_f32_e32 v61, v57, v57
	v_mul_f32_e32 v63, v59, v59
	s_waitcnt vmcnt(13)
	v_pk_add_f32 v[46:47], v[46:47], v[112:113]
	v_pk_add_f32 v[44:45], v[44:45], v[110:111]
	v_mul_f32_e32 v102, v49, v49
	v_mul_f32_e32 v103, v51, v51
	v_fmac_f32_e32 v100, v60, v60
	v_fmac_f32_e32 v101, v62, v62
	v_fmac_f32_e32 v61, v56, v56
	v_fmac_f32_e32 v63, v58, v58
	v_mul_f32_e32 v104, v45, v45
	v_mul_f32_e32 v105, v47, v47
	v_mov_b32_e32 v240, v98
	v_mov_b32_e32 v241, v99
	global_store_dwordx4 v[142:143], v[56:59], off offset:64
	v_fmac_f32_e32 v102, v48, v48
	v_fmac_f32_e32 v103, v50, v50
	v_cvt_pk_bf16_f32 v56, v56, v57
	v_cvt_pk_bf16_f32 v57, v58, v59
	v_add_f32_e32 v58, v100, v101
	v_add_f32_e32 v59, v61, v63
	v_fmac_f32_e32 v104, v44, v44
	v_fmac_f32_e32 v105, v46, v46
	v_mov_b32_e32 v242, v56
	v_mov_b32_e32 v243, v57
	v_mov_b32_dpp v242, v240 row_ror:8 row_mask:0xf bank_mask:0x3
	v_mov_b32_dpp v243, v241 row_ror:8 row_mask:0xf bank_mask:0x3
	v_mov_b32_dpp v240, v56 row_ror:8 row_mask:0xf bank_mask:0xc
	v_mov_b32_dpp v241, v57 row_ror:8 row_mask:0xf bank_mask:0xc
	v_ashrrev_i64 v[250:251], 1, v[254:255]
	v_lshl_add_u64 v[250:251], v[144:145], 0, v[250:251]
	v_lshl_add_u64 v[252:253], v[250:251], 0, s[100:101]
	global_store_dwordx2 v[250:251], v[240:241], off
	global_store_dwordx2 v[252:253], v[242:243], off
	global_store_dwordx4 v[142:143], v[48:51], off offset:512
	v_add_f32_e32 v56, v102, v103
	s_waitcnt vmcnt(16)
	v_pk_add_f32 v[54:55], v[54:55], v[116:117]
	v_cvt_pk_bf16_f32 v48, v48, v49
	v_cvt_pk_bf16_f32 v49, v50, v51
	v_add_f32_e32 v51, v58, v59
	v_add_f32_e32 v50, v104, v105
	v_mov_b32_e32 v240, v48
	v_mov_b32_e32 v241, v49
	global_store_dwordx4 v[142:143], v[44:47], off offset:576
	v_pk_add_f32 v[52:53], v[52:53], v[114:115]
	s_waitcnt vmcnt(16)
	v_pk_add_f32 v[40:41], v[40:41], v[118:119]
	v_cvt_pk_bf16_f32 v44, v44, v45
	v_cvt_pk_bf16_f32 v45, v46, v47
	v_add_f32_e32 v46, v51, v56
	v_mov_b32_e32 v242, v44
	v_mov_b32_e32 v243, v45
	v_mov_b32_dpp v242, v240 row_ror:8 row_mask:0xf bank_mask:0x3
	v_mov_b32_dpp v243, v241 row_ror:8 row_mask:0xf bank_mask:0x3
	v_mov_b32_dpp v240, v44 row_ror:8 row_mask:0xf bank_mask:0xc
	v_mov_b32_dpp v241, v45 row_ror:8 row_mask:0xf bank_mask:0xc
	v_ashrrev_i64 v[250:251], 1, v[254:255]
	v_lshl_add_u64 v[250:251], v[144:145], 0, v[250:251]
	v_lshl_add_u64 v[252:253], v[250:251], 0, s[100:101]
	global_store_dwordx2 v[250:251], v[240:241], off offset:256
	global_store_dwordx2 v[252:253], v[242:243], off offset:256
	global_store_dwordx4 v[92:93], v[52:55], off
	v_add_f32_e32 v48, v46, v50
	v_cvt_pk_bf16_f32 v44, v52, v53
	v_lshl_add_u64 v[46:47], v[146:147], 1, s[10:11]
	v_cvt_pk_bf16_f32 v45, v54, v55
	v_mov_b32_e32 v240, v44
	v_mov_b32_e32 v241, v45
	v_pk_add_f32 v[42:43], v[42:43], v[120:121]
	v_mul_f32_e32 v44, v41, v41
	global_store_dwordx4 v[92:93], v[40:43], off offset:64
	v_fmac_f32_e32 v44, v40, v40
	s_waitcnt vmcnt(19)
	v_pk_add_f32 v[36:37], v[36:37], v[122:123]
	v_cvt_pk_bf16_f32 v40, v40, v41
	v_cvt_pk_bf16_f32 v41, v42, v43
	v_mov_b32_e32 v242, v40
	v_mov_b32_e32 v243, v41
	v_mov_b32_dpp v242, v240 row_ror:8 row_mask:0xf bank_mask:0x3
	v_mov_b32_dpp v243, v241 row_ror:8 row_mask:0xf bank_mask:0x3
	v_mov_b32_dpp v240, v40 row_ror:8 row_mask:0xf bank_mask:0xc
	v_mov_b32_dpp v241, v41 row_ror:8 row_mask:0xf bank_mask:0xc
	v_ashrrev_i64 v[250:251], 1, v[254:255]
	v_lshl_add_u64 v[250:251], v[46:47], 0, v[250:251]
	v_lshl_add_u64 v[252:253], v[250:251], 0, s[100:101]
	global_store_dwordx2 v[250:251], v[240:241], off
	global_store_dwordx2 v[252:253], v[242:243], off
	v_pk_add_f32 v[38:39], v[38:39], v[124:125]
	v_mul_f32_e32 v40, v37, v37
	global_store_dwordx4 v[92:93], v[36:39], off offset:512
	v_fmac_f32_e32 v40, v36, v36
	s_waitcnt vmcnt(21)
	v_pk_add_f32 v[32:33], v[32:33], v[126:127]
	v_cvt_pk_bf16_f32 v36, v36, v37
	v_cvt_pk_bf16_f32 v37, v38, v39
	v_mov_b32_e32 v240, v36
	v_mov_b32_e32 v241, v37
	v_pk_add_f32 v[34:35], v[34:35], v[128:129]
	v_mul_f32_e32 v36, v33, v33
	global_store_dwordx4 v[92:93], v[32:35], off offset:576
	v_fmac_f32_e32 v36, v32, v32
	v_mul_f32_e32 v37, v35, v35
	v_cvt_pk_bf16_f32 v32, v32, v33
	v_cvt_pk_bf16_f32 v33, v34, v35
	v_mov_b32_e32 v242, v32
	v_mov_b32_e32 v243, v33
	v_mov_b32_dpp v242, v240 row_ror:8 row_mask:0xf bank_mask:0x3
	v_mov_b32_dpp v243, v241 row_ror:8 row_mask:0xf bank_mask:0x3
	v_mov_b32_dpp v240, v32 row_ror:8 row_mask:0xf bank_mask:0xc
	v_mov_b32_dpp v241, v33 row_ror:8 row_mask:0xf bank_mask:0xc
	v_ashrrev_i64 v[250:251], 1, v[254:255]
	v_lshl_add_u64 v[250:251], v[46:47], 0, v[250:251]
	v_lshl_add_u64 v[252:253], v[250:251], 0, s[100:101]
	global_store_dwordx2 v[250:251], v[240:241], off offset:256
	global_store_dwordx2 v[252:253], v[242:243], off offset:256
	v_lshlrev_b64 v[32:33], 11, v[90:91]
	s_waitcnt vmcnt(23)
	v_pk_add_f32 v[30:31], v[30:31], v[132:133]
	v_pk_add_f32 v[28:29], v[28:29], v[130:131]
	v_fmac_f32_e32 v37, v34, v34
	v_lshl_add_u64 v[32:33], v[32:33], 0, v[164:165]
	v_mul_f32_e32 v34, v29, v29
	v_mul_f32_e32 v35, v31, v31
	global_store_dwordx4 v[94:95], v[28:31], off
	v_fmac_f32_e32 v34, v28, v28
	v_fmac_f32_e32 v35, v30, v30
	v_cvt_pk_bf16_f32 v28, v28, v29
	v_cvt_pk_bf16_f32 v29, v30, v31
	v_lshl_add_u64 v[30:31], v[32:33], 1, s[10:11]
	s_waitcnt vmcnt(23)
	v_pk_add_f32 v[24:25], v[24:25], v[134:135]
	v_mov_b32_e32 v240, v28
	v_mov_b32_e32 v241, v29
	v_pk_add_f32 v[26:27], v[26:27], v[136:137]
	v_mul_f32_e32 v28, v25, v25
	global_store_dwordx4 v[94:95], v[24:27], off offset:64
	v_fmac_f32_e32 v28, v24, v24
	s_waitcnt vmcnt(23)
	v_pk_add_f32 v[20:21], v[20:21], v[138:139]
	v_cvt_pk_bf16_f32 v24, v24, v25
	v_cvt_pk_bf16_f32 v25, v26, v27
	v_mov_b32_e32 v242, v24
	v_mov_b32_e32 v243, v25
	v_mov_b32_dpp v242, v240 row_ror:8 row_mask:0xf bank_mask:0x3
	v_mov_b32_dpp v243, v241 row_ror:8 row_mask:0xf bank_mask:0x3
	v_mov_b32_dpp v240, v24 row_ror:8 row_mask:0xf bank_mask:0xc
	v_mov_b32_dpp v241, v25 row_ror:8 row_mask:0xf bank_mask:0xc
	v_ashrrev_i64 v[250:251], 1, v[254:255]
	v_lshl_add_u64 v[250:251], v[30:31], 0, v[250:251]
	v_lshl_add_u64 v[252:253], v[250:251], 0, s[100:101]
	global_store_dwordx2 v[250:251], v[240:241], off
	global_store_dwordx2 v[252:253], v[242:243], off
	v_pk_add_f32 v[22:23], v[22:23], v[140:141]
	v_mul_f32_e32 v24, v21, v21
	global_store_dwordx4 v[94:95], v[20:23], off offset:512
	v_fmac_f32_e32 v24, v20, v20
	s_waitcnt vmcnt(25)
	v_pk_add_f32 v[16:17], v[16:17], v[80:81]
	v_cvt_pk_bf16_f32 v20, v20, v21
	v_cvt_pk_bf16_f32 v21, v22, v23
	v_mov_b32_e32 v240, v20
	v_mov_b32_e32 v241, v21
	v_pk_add_f32 v[18:19], v[18:19], v[82:83]
	v_mul_f32_e32 v20, v17, v17
	global_store_dwordx4 v[94:95], v[16:19], off offset:576
	v_fmac_f32_e32 v20, v16, v16
	v_mul_f32_e32 v21, v19, v19
	v_cvt_pk_bf16_f32 v16, v16, v17
	v_cvt_pk_bf16_f32 v17, v18, v19
	v_mov_b32_e32 v242, v16
	v_mov_b32_e32 v243, v17
	v_mov_b32_dpp v242, v240 row_ror:8 row_mask:0xf bank_mask:0x3
	v_mov_b32_dpp v243, v241 row_ror:8 row_mask:0xf bank_mask:0x3
	v_mov_b32_dpp v240, v16 row_ror:8 row_mask:0xf bank_mask:0xc
	v_mov_b32_dpp v241, v17 row_ror:8 row_mask:0xf bank_mask:0xc
	v_ashrrev_i64 v[250:251], 1, v[254:255]
	v_lshl_add_u64 v[250:251], v[30:31], 0, v[250:251]
	v_lshl_add_u64 v[252:253], v[250:251], 0, s[100:101]
	global_store_dwordx2 v[250:251], v[240:241], off offset:256
	global_store_dwordx2 v[252:253], v[242:243], off offset:256
	v_lshlrev_b64 v[16:17], 11, v[88:89]
	s_waitcnt vmcnt(27)
	v_pk_add_f32 v[14:15], v[14:15], v[78:79]
	v_pk_add_f32 v[12:13], v[12:13], v[76:77]
	v_fmac_f32_e32 v21, v18, v18
	v_lshl_add_u64 v[16:17], v[16:17], 0, v[164:165]
	v_mul_f32_e32 v18, v13, v13
	v_mul_f32_e32 v19, v15, v15
	global_store_dwordx4 v[86:87], v[12:15], off
	v_fmac_f32_e32 v18, v12, v12
	v_fmac_f32_e32 v19, v14, v14
	v_cvt_pk_bf16_f32 v12, v12, v13
	v_cvt_pk_bf16_f32 v13, v14, v15
	v_lshl_add_u64 v[14:15], v[16:17], 1, s[10:11]
	s_waitcnt vmcnt(27)
	v_pk_add_f32 v[8:9], v[8:9], v[72:73]
	v_mov_b32_e32 v240, v12
	v_mov_b32_e32 v241, v13
	v_pk_add_f32 v[10:11], v[10:11], v[74:75]
	v_mul_f32_e32 v12, v9, v9
	global_store_dwordx4 v[86:87], v[8:11], off offset:64
	v_fmac_f32_e32 v12, v8, v8
	v_mul_f32_e32 v13, v11, v11
	v_cvt_pk_bf16_f32 v8, v8, v9
	v_cvt_pk_bf16_f32 v9, v10, v11
	s_waitcnt vmcnt(27)
	v_pk_add_f32 v[6:7], v[6:7], v[70:71]
	v_pk_add_f32 v[4:5], v[4:5], v[68:69]
	v_fmac_f32_e32 v13, v10, v10
	v_mov_b32_e32 v242, v8
	v_mov_b32_e32 v243, v9
	v_mov_b32_dpp v242, v240 row_ror:8 row_mask:0xf bank_mask:0x3
	v_mov_b32_dpp v243, v241 row_ror:8 row_mask:0xf bank_mask:0x3
	v_mov_b32_dpp v240, v8 row_ror:8 row_mask:0xf bank_mask:0xc
	v_mov_b32_dpp v241, v9 row_ror:8 row_mask:0xf bank_mask:0xc
	v_ashrrev_i64 v[250:251], 1, v[254:255]
	v_lshl_add_u64 v[250:251], v[14:15], 0, v[250:251]
	v_lshl_add_u64 v[252:253], v[250:251], 0, s[100:101]
	global_store_dwordx2 v[250:251], v[240:241], off
	global_store_dwordx2 v[252:253], v[242:243], off
	v_mul_f32_e32 v8, v5, v5
	v_mul_f32_e32 v9, v7, v7
	v_add_f32_e32 v18, v18, v19
	v_add_f32_e32 v12, v12, v13
	v_fmac_f32_e32 v8, v4, v4
	v_fmac_f32_e32 v9, v6, v6
	v_mul_f32_e32 v106, v53, v53
	v_mul_f32_e32 v107, v55, v55
	v_mul_f32_e32 v45, v43, v43
	v_mul_f32_e32 v29, v27, v27
	v_add_f32_e32 v12, v18, v12
	v_add_f32_e32 v8, v8, v9
	v_fmac_f32_e32 v106, v52, v52
	v_fmac_f32_e32 v107, v54, v54
	v_fmac_f32_e32 v45, v42, v42
	v_mul_f32_e32 v41, v39, v39
	v_fmac_f32_e32 v29, v26, v26
	v_mul_f32_e32 v25, v23, v23
	v_add_f32_e32 v12, v12, v8
	s_waitcnt vmcnt(28)
	v_pk_add_f32 v[10:11], v[2:3], v[66:67]
	v_pk_add_f32 v[8:9], v[0:1], v[64:65]
	v_add_f32_e32 v49, v106, v107
	v_add_f32_e32 v44, v44, v45
	v_fmac_f32_e32 v41, v38, v38
	v_add_f32_e32 v34, v34, v35
	v_add_f32_e32 v28, v28, v29
	v_fmac_f32_e32 v25, v22, v22
	v_mul_f32_e32 v0, v9, v9
	v_mul_f32_e32 v1, v11, v11
	v_add_f32_e32 v44, v49, v44
	v_add_f32_e32 v40, v40, v41
	v_add_f32_e32 v28, v34, v28
	v_add_f32_e32 v24, v24, v25
	v_fmac_f32_e32 v0, v8, v8
	v_fmac_f32_e32 v1, v10, v10
	v_add_f32_e32 v40, v44, v40
	v_add_f32_e32 v36, v36, v37
	v_add_f32_e32 v24, v28, v24
	v_add_f32_e32 v20, v20, v21
	v_add_f32_e32 v0, v0, v1
	v_add_f32_e32 v36, v40, v36
	v_add_f32_e32 v20, v24, v20
	v_add_f32_e32 v3, v12, v0
	global_store_dwordx4 v[86:87], v[4:7], off offset:512
	ds_bpermute_b32 v0, v96, v48
	ds_bpermute_b32 v1, v96, v36
	v_cvt_pk_bf16_f32 v4, v4, v5
	v_cvt_pk_bf16_f32 v5, v6, v7
	ds_bpermute_b32 v2, v96, v20
	ds_bpermute_b32 v6, v96, v3
	v_mov_b32_e32 v240, v4
	v_mov_b32_e32 v241, v5
	s_waitcnt lgkmcnt(3)
	v_add_f32_e32 v0, v48, v0
	s_waitcnt lgkmcnt(2)
	v_add_f32_e32 v1, v36, v1
	s_waitcnt lgkmcnt(1)
	v_add_f32_e32 v2, v20, v2
	s_waitcnt lgkmcnt(0)
	v_add_f32_e32 v4, v3, v6
	ds_bpermute_b32 v3, v97, v0
	ds_bpermute_b32 v5, v97, v1
	ds_bpermute_b32 v6, v97, v2
	ds_bpermute_b32 v7, v97, v4
	global_store_dwordx4 v[86:87], v[8:11], off offset:576
	s_nop 1
	v_cvt_pk_bf16_f32 v8, v8, v9
	v_cvt_pk_bf16_f32 v9, v10, v11
	v_mov_b32_e32 v242, v8
	v_mov_b32_e32 v243, v9
	v_mov_b32_dpp v242, v240 row_ror:8 row_mask:0xf bank_mask:0x3
	v_mov_b32_dpp v243, v241 row_ror:8 row_mask:0xf bank_mask:0x3
	v_mov_b32_dpp v240, v8 row_ror:8 row_mask:0xf bank_mask:0xc
	v_mov_b32_dpp v241, v9 row_ror:8 row_mask:0xf bank_mask:0xc
	v_ashrrev_i64 v[250:251], 1, v[254:255]
	v_lshl_add_u64 v[250:251], v[14:15], 0, v[250:251]
	v_lshl_add_u64 v[252:253], v[250:251], 0, s[100:101]
	global_store_dwordx2 v[250:251], v[240:241], off offset:256
	global_store_dwordx2 v[252:253], v[242:243], off offset:256
	s_and_saveexec_b64 s[6:7], s[2:3]
	s_cbranch_execz .LBB0_1480
	s_waitcnt lgkmcnt(3)
	v_add_f32_e32 v0, v0, v3
	s_waitcnt lgkmcnt(0)
	v_add_f32_e32 v4, v4, v7
	v_add_f32_e32 v2, v2, v6
	v_add_f32_e32 v1, v1, v5
	global_atomic_add_f32 v[84:85], v0, off offset:512
	global_atomic_add_f32 v[84:85], v1, off offset:576
	global_atomic_add_f32 v[84:85], v2, off offset:640
	global_atomic_add_f32 v[84:85], v4, off offset:704
